# mid-segment s_setprio 0/1 pair between the two MFMA blocks removed in all live K-loops (MFMA stream uninterrupted), on top of the loop-edge variants
# speedup vs baseline: 1.0025x; 1.0001x over previous
.Lt13a_0:
	s_cmp_lg_u32 s100, 0
	s_cbranch_scc1 .Lt13b_0
	v_mfma_f32_16x16x32_bf16 v[120:123], v[160:163], v[176:179], v[120:123]
	v_mfma_f32_16x16x32_bf16 v[120:123], v[164:167], v[180:183], v[120:123]
	v_mfma_f32_16x16x32_bf16 v[104:107], v[160:163], v[184:187], v[104:107]
	v_mfma_f32_16x16x32_bf16 v[104:107], v[164:167], v[188:191], v[104:107]
	v_mfma_f32_16x16x32_bf16 v[88:91], v[160:163], v[192:195], v[88:91]
	v_mfma_f32_16x16x32_bf16 v[88:91], v[164:167], v[196:199], v[88:91]
	v_mfma_f32_16x16x32_bf16 v[72:75], v[160:163], v[200:203], v[72:75]
	v_mfma_f32_16x16x32_bf16 v[72:75], v[164:167], v[204:207], v[72:75]
	v_mfma_f32_16x16x32_bf16 v[68:71], v[168:171], v[200:203], v[68:71]
	v_mfma_f32_16x16x32_bf16 v[68:71], v[172:175], v[204:207], v[68:71]
	v_mfma_f32_16x16x32_bf16 v[84:87], v[168:171], v[192:195], v[84:87]
	v_mfma_f32_16x16x32_bf16 v[84:87], v[172:175], v[196:199], v[84:87]
	v_mfma_f32_16x16x32_bf16 v[100:103], v[168:171], v[184:187], v[100:103]
	v_mfma_f32_16x16x32_bf16 v[100:103], v[172:175], v[188:191], v[100:103]
	v_mfma_f32_16x16x32_bf16 v[116:119], v[168:171], v[176:179], v[116:119]
	v_mfma_f32_16x16x32_bf16 v[116:119], v[172:175], v[180:183], v[116:119]

.Lt13a_1:
	s_cmp_lg_u32 s100, 0
	s_cbranch_scc1 .Lt13b_1
	v_mfma_f32_16x16x32_bf16 v[56:59], v[160:163], v[176:179], v[56:59]
	v_mfma_f32_16x16x32_bf16 v[56:59], v[164:167], v[180:183], v[56:59]
	v_mfma_f32_16x16x32_bf16 v[40:43], v[160:163], v[184:187], v[40:43]
	v_mfma_f32_16x16x32_bf16 v[40:43], v[164:167], v[188:191], v[40:43]
	v_mfma_f32_16x16x32_bf16 v[24:27], v[160:163], v[192:195], v[24:27]
	v_mfma_f32_16x16x32_bf16 v[24:27], v[164:167], v[196:199], v[24:27]
	v_mfma_f32_16x16x32_bf16 v[8:11], v[160:163], v[200:203], v[8:11]
	v_mfma_f32_16x16x32_bf16 v[8:11], v[164:167], v[204:207], v[8:11]
	v_mfma_f32_16x16x32_bf16 v[4:7], v[168:171], v[200:203], v[4:7]
	v_mfma_f32_16x16x32_bf16 v[4:7], v[172:175], v[204:207], v[4:7]
	v_mfma_f32_16x16x32_bf16 v[20:23], v[168:171], v[192:195], v[20:23]
	v_mfma_f32_16x16x32_bf16 v[20:23], v[172:175], v[196:199], v[20:23]
	v_mfma_f32_16x16x32_bf16 v[36:39], v[168:171], v[184:187], v[36:39]
	v_mfma_f32_16x16x32_bf16 v[36:39], v[172:175], v[188:191], v[36:39]
	v_mfma_f32_16x16x32_bf16 v[52:55], v[168:171], v[176:179], v[52:55]
	v_mfma_f32_16x16x32_bf16 v[52:55], v[172:175], v[180:183], v[52:55]

.LBB0_1876:
	v_add_u32_e32 v2, s83, v144
	ds_read_b128 v[146:149], v2
	ds_read_b128 v[150:153], v2 offset:1024
	ds_read_b128 v[154:157], v2 offset:2048
	ds_read_b128 v[158:161], v2 offset:3072
	v_add_u32_e32 v2, s44, v144
	ds_read_b128 v[162:165], v2
	ds_read_b128 v[166:169], v2 offset:1024
	ds_read_b128 v[170:173], v2 offset:2048
	ds_read_b128 v[174:177], v2 offset:3072
	s_add_i32 s70, s18, 2
	s_add_u32 s71, s42, 0x80
	s_addc_u32 s19, s43, 0
	s_cmp_eq_u32 s57, s18
	s_cselect_b32 s18, s34, s71
	s_cselect_b32 s19, s35, s19
	s_cselect_b32 s77, s25, s69
	s_cselect_b32 s76, s24, s68
	v_lshl_add_u64 v[210:211], s[42:43], 0, v[140:141]
	s_add_i32 m0, s23, 0xc000
	ds_read_b128 v[178:181], v145
	ds_read_b128 v[182:185], v145 offset:1024
	ds_read_b128 v[186:189], v145 offset:2048
	ds_read_b128 v[190:193], v145 offset:3072
	ds_read_b128 v[194:197], v145 offset:4096
	ds_read_b128 v[198:201], v145 offset:5120
	ds_read_b128 v[202:205], v145 offset:6144
	ds_read_b128 v[206:209], v145 offset:7168
	global_load_lds_dwordx4 v[210:211], off
	v_lshl_add_u64 v[210:211], s[42:43], 0, v[142:143]
	s_add_i32 m0, s23, 0xe000
	s_nop 0
	global_load_lds_dwordx4 v[210:211], off
	s_setprio 1
	s_waitcnt vmcnt(8)
	s_waitcnt lgkmcnt(0)
	s_barrier
	v_mfma_f32_16x16x32_bf16 v[120:123], v[146:149], v[178:181], v[120:123]
	v_mfma_f32_16x16x32_bf16 v[120:123], v[150:153], v[182:185], v[120:123]
	v_mfma_f32_16x16x32_bf16 v[112:115], v[146:149], v[186:189], v[112:115]
	v_mfma_f32_16x16x32_bf16 v[112:115], v[150:153], v[190:193], v[112:115]
	v_mfma_f32_16x16x32_bf16 v[96:99], v[146:149], v[194:197], v[96:99]
	v_mfma_f32_16x16x32_bf16 v[96:99], v[150:153], v[198:201], v[96:99]
	v_mfma_f32_16x16x32_bf16 v[80:83], v[146:149], v[202:205], v[80:83]
	v_mfma_f32_16x16x32_bf16 v[80:83], v[150:153], v[206:209], v[80:83]
	v_mfma_f32_16x16x32_bf16 v[76:79], v[154:157], v[202:205], v[76:79]
	v_mfma_f32_16x16x32_bf16 v[76:79], v[158:161], v[206:209], v[76:79]
	v_mfma_f32_16x16x32_bf16 v[92:95], v[154:157], v[194:197], v[92:95]
	v_mfma_f32_16x16x32_bf16 v[92:95], v[158:161], v[198:201], v[92:95]
	v_mfma_f32_16x16x32_bf16 v[108:111], v[154:157], v[186:189], v[108:111]
	v_mfma_f32_16x16x32_bf16 v[108:111], v[158:161], v[190:193], v[108:111]
	v_mfma_f32_16x16x32_bf16 v[128:131], v[154:157], v[178:181], v[128:131]
	v_mfma_f32_16x16x32_bf16 v[128:131], v[158:161], v[182:185], v[128:131]
	v_mfma_f32_16x16x32_bf16 v[124:127], v[162:165], v[178:181], v[124:127]
	v_mfma_f32_16x16x32_bf16 v[124:127], v[166:169], v[182:185], v[124:127]
	v_mfma_f32_16x16x32_bf16 v[104:107], v[162:165], v[186:189], v[104:107]
	v_mfma_f32_16x16x32_bf16 v[104:107], v[166:169], v[190:193], v[104:107]
	v_mfma_f32_16x16x32_bf16 v[88:91], v[162:165], v[194:197], v[88:91]
	v_mfma_f32_16x16x32_bf16 v[88:91], v[166:169], v[198:201], v[88:91]
	v_mfma_f32_16x16x32_bf16 v[72:75], v[162:165], v[202:205], v[72:75]
	v_mfma_f32_16x16x32_bf16 v[72:75], v[166:169], v[206:209], v[72:75]
	v_mfma_f32_16x16x32_bf16 v[68:71], v[170:173], v[202:205], v[68:71]
	v_mfma_f32_16x16x32_bf16 v[68:71], v[174:177], v[206:209], v[68:71]
	v_mfma_f32_16x16x32_bf16 v[84:87], v[170:173], v[194:197], v[84:87]
	v_mfma_f32_16x16x32_bf16 v[84:87], v[174:177], v[198:201], v[84:87]
	v_mfma_f32_16x16x32_bf16 v[100:103], v[170:173], v[186:189], v[100:103]
	v_mfma_f32_16x16x32_bf16 v[100:103], v[174:177], v[190:193], v[100:103]
	v_mfma_f32_16x16x32_bf16 v[116:119], v[170:173], v[178:181], v[116:119]
	v_mfma_f32_16x16x32_bf16 v[116:119], v[174:177], v[182:185], v[116:119]
	s_barrier
	s_setprio 0
	s_mov_b32 m0, s16
	v_lshl_add_u64 v[210:211], s[76:77], 0, v[134:135]
	v_lshl_add_u64 v[216:217], s[76:77], 0, v[138:139]
	s_add_u32 s76, s76, s4
	ds_read_b128 v[178:181], v145 offset:16384
	ds_read_b128 v[182:185], v145 offset:17408
	ds_read_b128 v[186:189], v145 offset:18432
	ds_read_b128 v[190:193], v145 offset:19456
	ds_read_b128 v[194:197], v145 offset:20480
	ds_read_b128 v[198:201], v145 offset:21504
	ds_read_b128 v[202:205], v145 offset:22528
	ds_read_b128 v[206:209], v145 offset:23552
	global_load_lds_dwordx4 v[210:211], off
	s_mov_b32 m0, s20
	s_addc_u32 s77, s77, s5
	global_load_lds_dwordx4 v[216:217], off
	v_lshl_add_u64 v[218:219], s[76:77], 0, v[134:135]
	s_mov_b32 m0, s21
	v_lshl_add_u64 v[220:221], s[76:77], 0, v[138:139]
	global_load_lds_dwordx4 v[218:219], off
	s_mov_b32 m0, s22
	v_lshl_add_u64 v[222:223], s[18:19], 0, v[132:133]
	global_load_lds_dwordx4 v[220:221], off
	s_mov_b32 m0, s23
	v_lshl_add_u64 v[224:225], s[18:19], 0, v[136:137]
	global_load_lds_dwordx4 v[222:223], off
	s_mov_b32 m0, s26
	s_nop 0
	global_load_lds_dwordx4 v[224:225], off
	s_setprio 1
	s_waitcnt vmcnt(8)
	s_waitcnt lgkmcnt(0)
	s_barrier
	v_mfma_f32_16x16x32_bf16 v[64:67], v[146:149], v[178:181], v[64:67]
	v_mfma_f32_16x16x32_bf16 v[64:67], v[150:153], v[182:185], v[64:67]
	v_mfma_f32_16x16x32_bf16 v[48:51], v[146:149], v[186:189], v[48:51]
	v_mfma_f32_16x16x32_bf16 v[48:51], v[150:153], v[190:193], v[48:51]
	v_mfma_f32_16x16x32_bf16 v[32:35], v[146:149], v[194:197], v[32:35]
	v_mfma_f32_16x16x32_bf16 v[32:35], v[150:153], v[198:201], v[32:35]
	v_mfma_f32_16x16x32_bf16 v[16:19], v[146:149], v[202:205], v[16:19]
	v_mfma_f32_16x16x32_bf16 v[16:19], v[150:153], v[206:209], v[16:19]
	v_mfma_f32_16x16x32_bf16 v[12:15], v[154:157], v[202:205], v[12:15]
	v_mfma_f32_16x16x32_bf16 v[12:15], v[158:161], v[206:209], v[12:15]
	v_mfma_f32_16x16x32_bf16 v[28:31], v[154:157], v[194:197], v[28:31]
	v_mfma_f32_16x16x32_bf16 v[28:31], v[158:161], v[198:201], v[28:31]
	v_mfma_f32_16x16x32_bf16 v[44:47], v[154:157], v[186:189], v[44:47]
	v_mfma_f32_16x16x32_bf16 v[44:47], v[158:161], v[190:193], v[44:47]
	v_mfma_f32_16x16x32_bf16 v[60:63], v[154:157], v[178:181], v[60:63]
	v_mfma_f32_16x16x32_bf16 v[60:63], v[158:161], v[182:185], v[60:63]
	v_mfma_f32_16x16x32_bf16 v[56:59], v[162:165], v[178:181], v[56:59]
	v_mfma_f32_16x16x32_bf16 v[56:59], v[166:169], v[182:185], v[56:59]
	v_mfma_f32_16x16x32_bf16 v[40:43], v[162:165], v[186:189], v[40:43]
	v_mfma_f32_16x16x32_bf16 v[40:43], v[166:169], v[190:193], v[40:43]
	v_mfma_f32_16x16x32_bf16 v[24:27], v[162:165], v[194:197], v[24:27]
	v_mfma_f32_16x16x32_bf16 v[24:27], v[166:169], v[198:201], v[24:27]
	v_mfma_f32_16x16x32_bf16 v[8:11], v[162:165], v[202:205], v[8:11]
	v_mfma_f32_16x16x32_bf16 v[8:11], v[166:169], v[206:209], v[8:11]
	v_mfma_f32_16x16x32_bf16 v[4:7], v[170:173], v[202:205], v[4:7]
	v_mfma_f32_16x16x32_bf16 v[4:7], v[174:177], v[206:209], v[4:7]
	v_mfma_f32_16x16x32_bf16 v[20:23], v[170:173], v[194:197], v[20:23]
	v_mfma_f32_16x16x32_bf16 v[20:23], v[174:177], v[198:201], v[20:23]
	v_mfma_f32_16x16x32_bf16 v[36:39], v[170:173], v[186:189], v[36:39]
	v_mfma_f32_16x16x32_bf16 v[36:39], v[174:177], v[190:193], v[36:39]
	v_mfma_f32_16x16x32_bf16 v[52:55], v[170:173], v[178:181], v[52:55]
	v_mfma_f32_16x16x32_bf16 v[52:55], v[174:177], v[182:185], v[52:55]
	s_barrier
	s_setprio 0
	v_add_u32_e32 v2, s45, v144
	ds_read_b128 v[146:149], v2
	ds_read_b128 v[150:153], v2 offset:1024
	ds_read_b128 v[154:157], v2 offset:2048
	ds_read_b128 v[158:161], v2 offset:3072
	v_add_u32_e32 v2, s74, v144
	ds_read_b128 v[162:165], v2
	ds_read_b128 v[166:169], v2 offset:1024
	ds_read_b128 v[170:173], v2 offset:2048
	ds_read_b128 v[174:177], v2 offset:3072
	s_add_u32 s18, s18, s4
	s_addc_u32 s19, s19, s5
	s_mov_b32 m0, s27
	v_lshl_add_u64 v[226:227], s[18:19], 0, v[132:133]
	ds_read_b128 v[178:181], v145 offset:32768
	ds_read_b128 v[182:185], v145 offset:33792
	ds_read_b128 v[186:189], v145 offset:34816
	ds_read_b128 v[190:193], v145 offset:35840
	ds_read_b128 v[194:197], v145 offset:36864
	ds_read_b128 v[198:201], v145 offset:37888
	ds_read_b128 v[202:205], v145 offset:38912
	ds_read_b128 v[206:209], v145 offset:39936
	global_load_lds_dwordx4 v[226:227], off
	v_lshl_add_u64 v[226:227], s[18:19], 0, v[136:137]
	s_mov_b32 m0, s37
	s_nop 0
	global_load_lds_dwordx4 v[226:227], off
	s_setprio 1
	s_waitcnt vmcnt(8)
	s_waitcnt lgkmcnt(0)
	s_barrier
	v_mfma_f32_16x16x32_bf16 v[120:123], v[146:149], v[178:181], v[120:123]
	v_mfma_f32_16x16x32_bf16 v[120:123], v[150:153], v[182:185], v[120:123]
	v_mfma_f32_16x16x32_bf16 v[112:115], v[146:149], v[186:189], v[112:115]
	v_mfma_f32_16x16x32_bf16 v[112:115], v[150:153], v[190:193], v[112:115]
	v_mfma_f32_16x16x32_bf16 v[96:99], v[146:149], v[194:197], v[96:99]
	v_mfma_f32_16x16x32_bf16 v[96:99], v[150:153], v[198:201], v[96:99]
	v_mfma_f32_16x16x32_bf16 v[80:83], v[146:149], v[202:205], v[80:83]
	v_mfma_f32_16x16x32_bf16 v[80:83], v[150:153], v[206:209], v[80:83]
	v_mfma_f32_16x16x32_bf16 v[76:79], v[154:157], v[202:205], v[76:79]
	v_mfma_f32_16x16x32_bf16 v[76:79], v[158:161], v[206:209], v[76:79]
	v_mfma_f32_16x16x32_bf16 v[92:95], v[154:157], v[194:197], v[92:95]
	v_mfma_f32_16x16x32_bf16 v[92:95], v[158:161], v[198:201], v[92:95]
	v_mfma_f32_16x16x32_bf16 v[108:111], v[154:157], v[186:189], v[108:111]
	v_mfma_f32_16x16x32_bf16 v[108:111], v[158:161], v[190:193], v[108:111]
	v_mfma_f32_16x16x32_bf16 v[128:131], v[154:157], v[178:181], v[128:131]
	v_mfma_f32_16x16x32_bf16 v[128:131], v[158:161], v[182:185], v[128:131]
	v_mfma_f32_16x16x32_bf16 v[124:127], v[162:165], v[178:181], v[124:127]
	v_mfma_f32_16x16x32_bf16 v[124:127], v[166:169], v[182:185], v[124:127]
	v_mfma_f32_16x16x32_bf16 v[104:107], v[162:165], v[186:189], v[104:107]
	v_mfma_f32_16x16x32_bf16 v[104:107], v[166:169], v[190:193], v[104:107]
	v_mfma_f32_16x16x32_bf16 v[88:91], v[162:165], v[194:197], v[88:91]
	v_mfma_f32_16x16x32_bf16 v[88:91], v[166:169], v[198:201], v[88:91]
	v_mfma_f32_16x16x32_bf16 v[72:75], v[162:165], v[202:205], v[72:75]
	v_mfma_f32_16x16x32_bf16 v[72:75], v[166:169], v[206:209], v[72:75]
	v_mfma_f32_16x16x32_bf16 v[68:71], v[170:173], v[202:205], v[68:71]
	v_mfma_f32_16x16x32_bf16 v[68:71], v[174:177], v[206:209], v[68:71]
	v_mfma_f32_16x16x32_bf16 v[84:87], v[170:173], v[194:197], v[84:87]
	v_mfma_f32_16x16x32_bf16 v[84:87], v[174:177], v[198:201], v[84:87]
	v_mfma_f32_16x16x32_bf16 v[100:103], v[170:173], v[186:189], v[100:103]
	v_mfma_f32_16x16x32_bf16 v[100:103], v[174:177], v[190:193], v[100:103]
	v_mfma_f32_16x16x32_bf16 v[116:119], v[170:173], v[178:181], v[116:119]
	v_mfma_f32_16x16x32_bf16 v[116:119], v[174:177], v[182:185], v[116:119]
	s_barrier
	s_setprio 0
	s_mov_b32 m0, s49
	v_lshl_add_u64 v[210:211], v[210:211], 0, s[64:65]
	ds_read_b128 v[178:181], v145 offset:49152
	ds_read_b128 v[182:185], v145 offset:50176
	ds_read_b128 v[186:189], v145 offset:51200
	ds_read_b128 v[190:193], v145 offset:52224
	ds_read_b128 v[194:197], v145 offset:53248
	ds_read_b128 v[198:201], v145 offset:54272
	ds_read_b128 v[202:205], v145 offset:55296
	ds_read_b128 v[206:209], v145 offset:56320
	global_load_lds_dwordx4 v[210:211], off
	v_lshl_add_u64 v[210:211], v[216:217], 0, s[64:65]
	s_mov_b32 m0, s50
	s_nop 0
	global_load_lds_dwordx4 v[210:211], off
	v_lshl_add_u64 v[210:211], v[218:219], 0, s[64:65]
	s_mov_b32 m0, s53
	s_nop 0
	global_load_lds_dwordx4 v[210:211], off
	v_lshl_add_u64 v[210:211], v[220:221], 0, s[64:65]
	s_mov_b32 m0, s56
	s_nop 0
	global_load_lds_dwordx4 v[210:211], off
	v_lshl_add_u64 v[210:211], v[222:223], 0, s[64:65]
	s_mov_b32 m0, s51
	s_nop 0
	global_load_lds_dwordx4 v[210:211], off
	v_lshl_add_u64 v[210:211], v[224:225], 0, s[64:65]
	s_mov_b32 m0, s52
	s_nop 0
	global_load_lds_dwordx4 v[210:211], off
	s_setprio 1
	s_waitcnt vmcnt(8)
	s_waitcnt lgkmcnt(0)
	s_barrier
	v_mfma_f32_16x16x32_bf16 v[64:67], v[146:149], v[178:181], v[64:67]
	v_mfma_f32_16x16x32_bf16 v[64:67], v[150:153], v[182:185], v[64:67]
	v_mfma_f32_16x16x32_bf16 v[48:51], v[146:149], v[186:189], v[48:51]
	v_mfma_f32_16x16x32_bf16 v[48:51], v[150:153], v[190:193], v[48:51]
	v_mfma_f32_16x16x32_bf16 v[32:35], v[146:149], v[194:197], v[32:35]
	v_mfma_f32_16x16x32_bf16 v[32:35], v[150:153], v[198:201], v[32:35]
	v_mfma_f32_16x16x32_bf16 v[16:19], v[146:149], v[202:205], v[16:19]
	v_mfma_f32_16x16x32_bf16 v[16:19], v[150:153], v[206:209], v[16:19]
	v_mfma_f32_16x16x32_bf16 v[12:15], v[154:157], v[202:205], v[12:15]
	v_mfma_f32_16x16x32_bf16 v[12:15], v[158:161], v[206:209], v[12:15]
	v_mfma_f32_16x16x32_bf16 v[28:31], v[154:157], v[194:197], v[28:31]
	v_mfma_f32_16x16x32_bf16 v[28:31], v[158:161], v[198:201], v[28:31]
	v_mfma_f32_16x16x32_bf16 v[44:47], v[154:157], v[186:189], v[44:47]
	v_mfma_f32_16x16x32_bf16 v[44:47], v[158:161], v[190:193], v[44:47]
	v_mfma_f32_16x16x32_bf16 v[60:63], v[154:157], v[178:181], v[60:63]
	v_mfma_f32_16x16x32_bf16 v[60:63], v[158:161], v[182:185], v[60:63]
	v_mfma_f32_16x16x32_bf16 v[56:59], v[162:165], v[178:181], v[56:59]
	v_mfma_f32_16x16x32_bf16 v[56:59], v[166:169], v[182:185], v[56:59]
	v_mfma_f32_16x16x32_bf16 v[40:43], v[162:165], v[186:189], v[40:43]
	v_mfma_f32_16x16x32_bf16 v[40:43], v[166:169], v[190:193], v[40:43]
	v_mfma_f32_16x16x32_bf16 v[24:27], v[162:165], v[194:197], v[24:27]
	v_mfma_f32_16x16x32_bf16 v[24:27], v[166:169], v[198:201], v[24:27]
	v_mfma_f32_16x16x32_bf16 v[8:11], v[162:165], v[202:205], v[8:11]
	v_mfma_f32_16x16x32_bf16 v[8:11], v[166:169], v[206:209], v[8:11]
	s_add_u32 s42, s42, 0x100
	s_addc_u32 s43, s43, 0
	v_mfma_f32_16x16x32_bf16 v[4:7], v[170:173], v[202:205], v[4:7]
	v_mfma_f32_16x16x32_bf16 v[4:7], v[174:177], v[206:209], v[4:7]
	s_add_u32 s68, s68, 0x100
	s_addc_u32 s69, s69, 0
	v_mfma_f32_16x16x32_bf16 v[20:23], v[170:173], v[194:197], v[20:23]
	v_mfma_f32_16x16x32_bf16 v[20:23], v[174:177], v[198:201], v[20:23]
	s_cmp_ge_i32 s70, s46
	v_mfma_f32_16x16x32_bf16 v[36:39], v[170:173], v[186:189], v[36:39]
	v_mfma_f32_16x16x32_bf16 v[36:39], v[174:177], v[190:193], v[36:39]
	v_mfma_f32_16x16x32_bf16 v[52:55], v[170:173], v[178:181], v[52:55]
	v_mfma_f32_16x16x32_bf16 v[52:55], v[174:177], v[182:185], v[52:55]
	s_barrier
	s_setprio 0
	s_mov_b32 s18, s70
	s_cbranch_scc0 .LBB0_1876

.LBB0_1891:
	v_add_u32_e32 v2, s83, v189
	ds_read_b128 v[28:31], v2
	ds_read_b128 v[32:35], v2 offset:16
	ds_read_b128 v[20:23], v2 offset:2048
	ds_read_b128 v[24:27], v2 offset:2064
	v_add_u32_e32 v2, s44, v189
	ds_read_b128 v[12:15], v2
	ds_read_b128 v[16:19], v2 offset:16
	ds_read_b128 v[4:7], v2 offset:2048
	ds_read_b128 v[8:11], v2 offset:2064
	s_add_u32 s10, s8, 0xfffc0080
	s_addc_u32 s11, s9, -1
	s_cmp_eq_u32 s25, 12
	s_cselect_b32 s13, s3, s11
	s_cselect_b32 s12, s14, s10
	s_cselect_b32 s11, s15, s24
	s_cselect_b32 s10, s18, s19
	v_lshl_add_u64 v[208:209], s[8:9], 0, v[172:173]
	s_add_i32 m0, s16, 0xc000
	ds_read_b128 v[176:179], v191
	ds_read_b128 v[180:183], v191 offset:16
	ds_read_b128 v[192:195], v191 offset:2048
	ds_read_b128 v[196:199], v191 offset:2064
	ds_read_b128 v[200:203], v191 offset:4096
	ds_read_b128 v[204:207], v191 offset:4112
	ds_read_b128 v[216:219], v191 offset:6144
	ds_read_b128 v[220:223], v191 offset:6160
	global_load_lds_dwordx4 v[208:209], off
	v_lshl_add_u64 v[208:209], s[8:9], 0, v[174:175]
	s_add_i32 m0, s16, 0xe000
	s_nop 0
	global_load_lds_dwordx4 v[208:209], off
	s_setprio 1
	s_waitcnt vmcnt(8)
	s_waitcnt lgkmcnt(0)
	s_barrier
	v_mfma_scale_f32_16x16x128_f8f6f4 v[160:163], v[28:35], v[176:183], v[160:163], v187, v185 op_sel_hi:[0,0,0]
	v_mfma_scale_f32_16x16x128_f8f6f4 v[156:159], v[20:27], v[176:183], v[156:159], v187, v185 op_sel_hi:[0,0,0]
	v_mfma_scale_f32_16x16x128_f8f6f4 v[144:147], v[28:35], v[192:199], v[144:147], v187, v185 op_sel_hi:[0,0,0]
	v_mfma_scale_f32_16x16x128_f8f6f4 v[140:143], v[20:27], v[192:199], v[140:143], v187, v185 op_sel_hi:[0,0,0]
	v_mfma_scale_f32_16x16x128_f8f6f4 v[128:131], v[28:35], v[200:207], v[128:131], v187, v185 op_sel_hi:[0,0,0]
	v_mfma_scale_f32_16x16x128_f8f6f4 v[124:127], v[20:27], v[200:207], v[124:127], v187, v185 op_sel_hi:[0,0,0]
	v_mfma_scale_f32_16x16x128_f8f6f4 v[112:115], v[28:35], v[216:223], v[112:115], v187, v185 op_sel_hi:[0,0,0]
	v_mfma_scale_f32_16x16x128_f8f6f4 v[108:111], v[20:27], v[216:223], v[108:111], v187, v185 op_sel_hi:[0,0,0]
	v_mfma_scale_f32_16x16x128_f8f6f4 v[152:155], v[12:19], v[176:183], v[152:155], v187, v185 op_sel_hi:[0,0,0]
	v_mfma_scale_f32_16x16x128_f8f6f4 v[148:151], v[4:11], v[176:183], v[148:151], v187, v185 op_sel_hi:[0,0,0]
	v_mfma_scale_f32_16x16x128_f8f6f4 v[136:139], v[12:19], v[192:199], v[136:139], v187, v185 op_sel_hi:[0,0,0]
	v_mfma_scale_f32_16x16x128_f8f6f4 v[132:135], v[4:11], v[192:199], v[132:135], v187, v185 op_sel_hi:[0,0,0]
	v_mfma_scale_f32_16x16x128_f8f6f4 v[120:123], v[12:19], v[200:207], v[120:123], v187, v185 op_sel_hi:[0,0,0]
	v_mfma_scale_f32_16x16x128_f8f6f4 v[116:119], v[4:11], v[200:207], v[116:119], v187, v185 op_sel_hi:[0,0,0]
	v_mfma_scale_f32_16x16x128_f8f6f4 v[104:107], v[12:19], v[216:223], v[104:107], v187, v185 op_sel_hi:[0,0,0]
	v_mfma_scale_f32_16x16x128_f8f6f4 v[100:103], v[4:11], v[216:223], v[100:103], v187, v185 op_sel_hi:[0,0,0]
	s_barrier
	s_setprio 0
	s_mov_b32 m0, s22
	v_lshl_add_u64 v[176:177], s[10:11], 0, v[166:167]
	s_add_u32 s56, s10, 0x40000
	ds_read_b128 v[192:195], v191 offset:16384
	ds_read_b128 v[196:199], v191 offset:16400
	ds_read_b128 v[200:203], v191 offset:18432
	ds_read_b128 v[204:207], v191 offset:18448
	ds_read_b128 v[216:219], v191 offset:20480
	ds_read_b128 v[220:223], v191 offset:20496
	ds_read_b128 v[224:227], v191 offset:22528
	ds_read_b128 v[228:231], v191 offset:22544
	global_load_lds_dwordx4 v[176:177], off
	v_lshl_add_u64 v[178:179], s[10:11], 0, v[170:171]
	s_mov_b32 m0, s23
	s_addc_u32 s57, s11, 0
	global_load_lds_dwordx4 v[178:179], off
	v_lshl_add_u64 v[180:181], s[56:57], 0, v[166:167]
	s_mov_b32 m0, s75
	v_lshl_add_u64 v[182:183], s[12:13], 0, v[168:169]
	global_load_lds_dwordx4 v[180:181], off
	v_lshl_add_u64 v[180:181], s[56:57], 0, v[170:171]
	s_mov_b32 m0, s37
	s_nop 0
	global_load_lds_dwordx4 v[180:181], off
	v_lshl_add_u64 v[180:181], s[12:13], 0, v[164:165]
	s_mov_b32 m0, s16
	s_nop 0
	global_load_lds_dwordx4 v[180:181], off
	s_mov_b32 m0, s73
	s_nop 0
	global_load_lds_dwordx4 v[182:183], off
	s_setprio 1
	s_waitcnt vmcnt(8)
	s_waitcnt lgkmcnt(0)
	s_barrier
	v_mfma_scale_f32_16x16x128_f8f6f4 v[96:99], v[28:35], v[192:199], v[96:99], v187, v185 op_sel_hi:[0,0,0]
	v_mfma_scale_f32_16x16x128_f8f6f4 v[92:95], v[20:27], v[192:199], v[92:95], v187, v185 op_sel_hi:[0,0,0]
	v_mfma_scale_f32_16x16x128_f8f6f4 v[80:83], v[28:35], v[200:207], v[80:83], v187, v185 op_sel_hi:[0,0,0]
	v_mfma_scale_f32_16x16x128_f8f6f4 v[76:79], v[20:27], v[200:207], v[76:79], v187, v185 op_sel_hi:[0,0,0]
	v_mfma_scale_f32_16x16x128_f8f6f4 v[64:67], v[28:35], v[216:223], v[64:67], v187, v185 op_sel_hi:[0,0,0]
	v_mfma_scale_f32_16x16x128_f8f6f4 v[60:63], v[20:27], v[216:223], v[60:63], v187, v185 op_sel_hi:[0,0,0]
	v_mfma_scale_f32_16x16x128_f8f6f4 v[48:51], v[28:35], v[224:231], v[48:51], v187, v185 op_sel_hi:[0,0,0]
	v_mfma_scale_f32_16x16x128_f8f6f4 v[44:47], v[20:27], v[224:231], v[44:47], v187, v185 op_sel_hi:[0,0,0]
	v_mfma_scale_f32_16x16x128_f8f6f4 v[88:91], v[12:19], v[192:199], v[88:91], v187, v185 op_sel_hi:[0,0,0]
	v_mfma_scale_f32_16x16x128_f8f6f4 v[84:87], v[4:11], v[192:199], v[84:87], v187, v185 op_sel_hi:[0,0,0]
	v_mfma_scale_f32_16x16x128_f8f6f4 v[72:75], v[12:19], v[200:207], v[72:75], v187, v185 op_sel_hi:[0,0,0]
	v_mfma_scale_f32_16x16x128_f8f6f4 v[68:71], v[4:11], v[200:207], v[68:71], v187, v185 op_sel_hi:[0,0,0]
	v_mfma_scale_f32_16x16x128_f8f6f4 v[56:59], v[12:19], v[216:223], v[56:59], v187, v185 op_sel_hi:[0,0,0]
	v_mfma_scale_f32_16x16x128_f8f6f4 v[52:55], v[4:11], v[216:223], v[52:55], v187, v185 op_sel_hi:[0,0,0]
	v_mfma_scale_f32_16x16x128_f8f6f4 v[40:43], v[12:19], v[224:231], v[40:43], v187, v185 op_sel_hi:[0,0,0]
	v_mfma_scale_f32_16x16x128_f8f6f4 v[36:39], v[4:11], v[224:231], v[36:39], v187, v185 op_sel_hi:[0,0,0]
	s_barrier
	s_setprio 0
	v_add_u32_e32 v2, s45, v189
	ds_read_b128 v[28:31], v2
	ds_read_b128 v[32:35], v2 offset:16
	ds_read_b128 v[20:23], v2 offset:2048
	ds_read_b128 v[24:27], v2 offset:2064
	v_add_u32_e32 v2, s74, v189
	ds_read_b128 v[12:15], v2
	ds_read_b128 v[16:19], v2 offset:16
	ds_read_b128 v[4:7], v2 offset:2048
	ds_read_b128 v[8:11], v2 offset:2064
	s_add_u32 s12, s12, 0x40000
	s_addc_u32 s13, s13, 0
	s_mov_b32 m0, s82
	v_lshl_add_u64 v[208:209], s[12:13], 0, v[164:165]
	ds_read_b128 v[192:195], v191 offset:32768
	ds_read_b128 v[196:199], v191 offset:32784
	ds_read_b128 v[200:203], v191 offset:34816
	ds_read_b128 v[204:207], v191 offset:34832
	ds_read_b128 v[216:219], v191 offset:36864
	ds_read_b128 v[220:223], v191 offset:36880
	ds_read_b128 v[224:227], v191 offset:38912
	ds_read_b128 v[228:231], v191 offset:38928
	global_load_lds_dwordx4 v[208:209], off
	v_lshl_add_u64 v[208:209], s[12:13], 0, v[168:169]
	s_mov_b32 m0, s40
	s_nop 0
	global_load_lds_dwordx4 v[208:209], off
	s_setprio 1
	s_waitcnt vmcnt(8)
	s_waitcnt lgkmcnt(0)
	s_barrier
	v_mfma_scale_f32_16x16x128_f8f6f4 v[160:163], v[28:35], v[192:199], v[160:163], v187, v185 op_sel_hi:[0,0,0]
	v_mfma_scale_f32_16x16x128_f8f6f4 v[156:159], v[20:27], v[192:199], v[156:159], v187, v185 op_sel_hi:[0,0,0]
	v_mfma_scale_f32_16x16x128_f8f6f4 v[144:147], v[28:35], v[200:207], v[144:147], v187, v185 op_sel_hi:[0,0,0]
	v_mfma_scale_f32_16x16x128_f8f6f4 v[140:143], v[20:27], v[200:207], v[140:143], v187, v185 op_sel_hi:[0,0,0]
	v_mfma_scale_f32_16x16x128_f8f6f4 v[128:131], v[28:35], v[216:223], v[128:131], v187, v185 op_sel_hi:[0,0,0]
	v_mfma_scale_f32_16x16x128_f8f6f4 v[124:127], v[20:27], v[216:223], v[124:127], v187, v185 op_sel_hi:[0,0,0]
	v_mfma_scale_f32_16x16x128_f8f6f4 v[112:115], v[28:35], v[224:231], v[112:115], v187, v185 op_sel_hi:[0,0,0]
	v_mfma_scale_f32_16x16x128_f8f6f4 v[108:111], v[20:27], v[224:231], v[108:111], v187, v185 op_sel_hi:[0,0,0]
	v_mfma_scale_f32_16x16x128_f8f6f4 v[152:155], v[12:19], v[192:199], v[152:155], v187, v185 op_sel_hi:[0,0,0]
	v_mfma_scale_f32_16x16x128_f8f6f4 v[148:151], v[4:11], v[192:199], v[148:151], v187, v185 op_sel_hi:[0,0,0]
	v_mfma_scale_f32_16x16x128_f8f6f4 v[136:139], v[12:19], v[200:207], v[136:139], v187, v185 op_sel_hi:[0,0,0]
	v_mfma_scale_f32_16x16x128_f8f6f4 v[132:135], v[4:11], v[200:207], v[132:135], v187, v185 op_sel_hi:[0,0,0]
	v_mfma_scale_f32_16x16x128_f8f6f4 v[120:123], v[12:19], v[216:223], v[120:123], v187, v185 op_sel_hi:[0,0,0]
	v_mfma_scale_f32_16x16x128_f8f6f4 v[116:119], v[4:11], v[216:223], v[116:119], v187, v185 op_sel_hi:[0,0,0]
	v_mfma_scale_f32_16x16x128_f8f6f4 v[104:107], v[12:19], v[224:231], v[104:107], v187, v185 op_sel_hi:[0,0,0]
	v_mfma_scale_f32_16x16x128_f8f6f4 v[100:103], v[4:11], v[224:231], v[100:103], v187, v185 op_sel_hi:[0,0,0]
	s_barrier
	s_setprio 0
	s_mov_b32 m0, s49
	v_lshl_add_u64 v[176:177], v[176:177], 0, s[64:65]
	s_add_u32 s10, s10, 0x40080
	ds_read_b128 v[192:195], v191 offset:49152
	ds_read_b128 v[196:199], v191 offset:49168
	ds_read_b128 v[200:203], v191 offset:51200
	ds_read_b128 v[204:207], v191 offset:51216
	ds_read_b128 v[216:219], v191 offset:53248
	ds_read_b128 v[220:223], v191 offset:53264
	ds_read_b128 v[224:227], v191 offset:55296
	ds_read_b128 v[228:231], v191 offset:55312
	global_load_lds_dwordx4 v[176:177], off
	v_lshl_add_u64 v[176:177], v[178:179], 0, s[64:65]
	s_mov_b32 m0, s84
	s_addc_u32 s11, s11, 0
	global_load_lds_dwordx4 v[176:177], off
	v_lshl_add_u64 v[176:177], s[10:11], 0, v[166:167]
	s_mov_b32 m0, s27
	s_nop 0
	global_load_lds_dwordx4 v[176:177], off
	v_lshl_add_u64 v[176:177], s[10:11], 0, v[170:171]
	s_mov_b32 m0, s48
	s_nop 0
	global_load_lds_dwordx4 v[176:177], off
	v_lshl_add_u64 v[176:177], v[180:181], 0, s[64:65]
	s_mov_b32 m0, s85
	s_nop 0
	global_load_lds_dwordx4 v[176:177], off
	v_lshl_add_u64 v[176:177], v[182:183], 0, s[64:65]
	s_mov_b32 m0, s26
	s_nop 0
	global_load_lds_dwordx4 v[176:177], off
	s_setprio 1
	s_waitcnt vmcnt(8)
	s_waitcnt lgkmcnt(0)
	s_barrier
	v_mfma_scale_f32_16x16x128_f8f6f4 v[96:99], v[28:35], v[192:199], v[96:99], v187, v185 op_sel_hi:[0,0,0]
	v_mfma_scale_f32_16x16x128_f8f6f4 v[92:95], v[20:27], v[192:199], v[92:95], v187, v185 op_sel_hi:[0,0,0]
	v_mfma_scale_f32_16x16x128_f8f6f4 v[80:83], v[28:35], v[200:207], v[80:83], v187, v185 op_sel_hi:[0,0,0]
	v_mfma_scale_f32_16x16x128_f8f6f4 v[76:79], v[20:27], v[200:207], v[76:79], v187, v185 op_sel_hi:[0,0,0]
	v_mfma_scale_f32_16x16x128_f8f6f4 v[64:67], v[28:35], v[216:223], v[64:67], v187, v185 op_sel_hi:[0,0,0]
	v_mfma_scale_f32_16x16x128_f8f6f4 v[60:63], v[20:27], v[216:223], v[60:63], v187, v185 op_sel_hi:[0,0,0]
	v_mfma_scale_f32_16x16x128_f8f6f4 v[48:51], v[28:35], v[224:231], v[48:51], v187, v185 op_sel_hi:[0,0,0]
	v_mfma_scale_f32_16x16x128_f8f6f4 v[44:47], v[20:27], v[224:231], v[44:47], v187, v185 op_sel_hi:[0,0,0]
	v_mfma_scale_f32_16x16x128_f8f6f4 v[88:91], v[12:19], v[192:199], v[88:91], v187, v185 op_sel_hi:[0,0,0]
	v_mfma_scale_f32_16x16x128_f8f6f4 v[84:87], v[4:11], v[192:199], v[84:87], v187, v185 op_sel_hi:[0,0,0]
	v_mfma_scale_f32_16x16x128_f8f6f4 v[72:75], v[12:19], v[200:207], v[72:75], v187, v185 op_sel_hi:[0,0,0]
	v_mfma_scale_f32_16x16x128_f8f6f4 v[68:71], v[4:11], v[200:207], v[68:71], v187, v185 op_sel_hi:[0,0,0]
	s_add_i32 s25, s25, 2
	v_mfma_scale_f32_16x16x128_f8f6f4 v[56:59], v[12:19], v[216:223], v[56:59], v187, v185 op_sel_hi:[0,0,0]
	s_add_u32 s8, s8, 0x100
	s_addc_u32 s9, s9, 0
	v_mfma_scale_f32_16x16x128_f8f6f4 v[52:55], v[4:11], v[216:223], v[52:55], v187, v185 op_sel_hi:[0,0,0]
	s_add_u32 s19, s19, 0x100
	s_addc_u32 s24, s24, 0
	v_mfma_scale_f32_16x16x128_f8f6f4 v[40:43], v[12:19], v[224:231], v[40:43], v187, v185 op_sel_hi:[0,0,0]
	s_cmp_gt_u32 s25, 13
	v_mfma_scale_f32_16x16x128_f8f6f4 v[36:39], v[4:11], v[224:231], v[36:39], v187, v185 op_sel_hi:[0,0,0]
	s_barrier
	s_setprio 0
	s_cbranch_scc0 .LBB0_1891
	v_readlane_b32 s8, v255, 13
	v_readlane_b32 s9, v255, 14
	s_and_b64 vcc, exec, s[8:9]
	s_cbranch_vccz .LBB0_1894
	s_barrier

.LBB0_2329:
	s_add_i32 s43, s12, 2
	v_add_u32_e32 v156, s83, v142
	v_add_u32_e32 v172, s44, v142
	s_add_u32 s10, s8, 0x100
	ds_read_b128 v[144:147], v156
	ds_read_b128 v[148:151], v156 offset:1024
	ds_read_b128 v[152:155], v156 offset:2048
	ds_read_b128 v[156:159], v156 offset:3072
	ds_read_b128 v[160:163], v172
	ds_read_b128 v[164:167], v172 offset:1024
	ds_read_b128 v[168:171], v172 offset:2048
	ds_read_b128 v[172:175], v172 offset:3072
	s_addc_u32 s11, s9, 0
	s_cmp_lg_u32 s42, s12
	s_cselect_b32 s46, s10, 0
	s_cselect_b32 s47, s11, 0
	s_add_u32 s12, s6, s46
	s_addc_u32 s13, s7, s47
	s_add_u32 s46, s4, s46
	s_addc_u32 s47, s5, s47
	v_lshl_add_u64 v[208:209], v[138:139], 0, s[8:9]
	s_add_i32 m0, s22, 0xc000
	ds_read_b128 v[176:179], v143
	ds_read_b128 v[180:183], v143 offset:1024
	ds_read_b128 v[184:187], v143 offset:2048
	ds_read_b128 v[188:191], v143 offset:3072
	ds_read_b128 v[192:195], v143 offset:4096
	ds_read_b128 v[196:199], v143 offset:5120
	ds_read_b128 v[200:203], v143 offset:6144
	ds_read_b128 v[204:207], v143 offset:7168
	global_load_lds_dwordx4 v[208:209], off
	v_lshl_add_u64 v[208:209], v[140:141], 0, s[8:9]
	s_add_i32 m0, s22, 0xe000
	s_nop 0
	global_load_lds_dwordx4 v[208:209], off
	s_setprio 1
	s_waitcnt vmcnt(8)
	s_waitcnt lgkmcnt(0)
	s_barrier
	v_mfma_f32_16x16x32_bf16 v[124:127], v[144:147], v[176:179], v[124:127]
	v_mfma_f32_16x16x32_bf16 v[124:127], v[148:151], v[180:183], v[124:127]
	v_mfma_f32_16x16x32_bf16 v[112:115], v[144:147], v[184:187], v[112:115]
	v_mfma_f32_16x16x32_bf16 v[112:115], v[148:151], v[188:191], v[112:115]
	v_mfma_f32_16x16x32_bf16 v[96:99], v[144:147], v[192:195], v[96:99]
	v_mfma_f32_16x16x32_bf16 v[96:99], v[148:151], v[196:199], v[96:99]
	v_mfma_f32_16x16x32_bf16 v[80:83], v[144:147], v[200:203], v[80:83]
	v_mfma_f32_16x16x32_bf16 v[80:83], v[148:151], v[204:207], v[80:83]
	v_mfma_f32_16x16x32_bf16 v[76:79], v[152:155], v[200:203], v[76:79]
	v_mfma_f32_16x16x32_bf16 v[76:79], v[156:159], v[204:207], v[76:79]
	v_mfma_f32_16x16x32_bf16 v[92:95], v[152:155], v[192:195], v[92:95]
	v_mfma_f32_16x16x32_bf16 v[92:95], v[156:159], v[196:199], v[92:95]
	v_mfma_f32_16x16x32_bf16 v[108:111], v[152:155], v[184:187], v[108:111]
	v_mfma_f32_16x16x32_bf16 v[108:111], v[156:159], v[188:191], v[108:111]
	v_mfma_f32_16x16x32_bf16 v[128:131], v[152:155], v[176:179], v[128:131]
	v_mfma_f32_16x16x32_bf16 v[128:131], v[156:159], v[180:183], v[128:131]
	v_mfma_f32_16x16x32_bf16 v[120:123], v[160:163], v[176:179], v[120:123]
	v_mfma_f32_16x16x32_bf16 v[120:123], v[164:167], v[180:183], v[120:123]
	v_mfma_f32_16x16x32_bf16 v[104:107], v[160:163], v[184:187], v[104:107]
	v_mfma_f32_16x16x32_bf16 v[104:107], v[164:167], v[188:191], v[104:107]
	v_mfma_f32_16x16x32_bf16 v[88:91], v[160:163], v[192:195], v[88:91]
	v_mfma_f32_16x16x32_bf16 v[88:91], v[164:167], v[196:199], v[88:91]
	v_mfma_f32_16x16x32_bf16 v[72:75], v[160:163], v[200:203], v[72:75]
	v_mfma_f32_16x16x32_bf16 v[72:75], v[164:167], v[204:207], v[72:75]
	v_mfma_f32_16x16x32_bf16 v[68:71], v[168:171], v[200:203], v[68:71]
	v_mfma_f32_16x16x32_bf16 v[68:71], v[172:175], v[204:207], v[68:71]
	v_mfma_f32_16x16x32_bf16 v[84:87], v[168:171], v[192:195], v[84:87]
	v_mfma_f32_16x16x32_bf16 v[84:87], v[172:175], v[196:199], v[84:87]
	v_mfma_f32_16x16x32_bf16 v[100:103], v[168:171], v[184:187], v[100:103]
	v_mfma_f32_16x16x32_bf16 v[100:103], v[172:175], v[188:191], v[100:103]
	v_mfma_f32_16x16x32_bf16 v[116:119], v[168:171], v[176:179], v[116:119]
	v_mfma_f32_16x16x32_bf16 v[116:119], v[172:175], v[180:183], v[116:119]
	s_barrier
	s_setprio 0
	s_mov_b32 m0, s18
	v_lshl_add_u64 v[208:209], s[46:47], 0, v[2:3]
	s_add_u32 s8, s46, s2
	ds_read_b128 v[176:179], v143 offset:16384
	ds_read_b128 v[180:183], v143 offset:17408
	ds_read_b128 v[184:187], v143 offset:18432
	ds_read_b128 v[188:191], v143 offset:19456
	ds_read_b128 v[192:195], v143 offset:20480
	ds_read_b128 v[196:199], v143 offset:21504
	ds_read_b128 v[200:203], v143 offset:22528
	ds_read_b128 v[204:207], v143 offset:23552
	global_load_lds_dwordx4 v[208:209], off
	v_lshl_add_u64 v[210:211], s[46:47], 0, v[136:137]
	s_mov_b32 m0, s19
	s_addc_u32 s9, s47, s3
	global_load_lds_dwordx4 v[210:211], off
	v_lshl_add_u64 v[216:217], s[8:9], 0, v[2:3]
	s_mov_b32 m0, s20
	v_lshl_add_u64 v[218:219], s[8:9], 0, v[136:137]
	global_load_lds_dwordx4 v[216:217], off
	s_mov_b32 m0, s21
	v_lshl_add_u64 v[220:221], s[12:13], 0, v[132:133]
	global_load_lds_dwordx4 v[218:219], off
	s_mov_b32 m0, s22
	v_lshl_add_u64 v[222:223], s[12:13], 0, v[134:135]
	global_load_lds_dwordx4 v[220:221], off
	s_mov_b32 m0, s23
	s_nop 0
	global_load_lds_dwordx4 v[222:223], off
	s_setprio 1
	s_waitcnt vmcnt(8)
	s_waitcnt lgkmcnt(0)
	s_barrier
	v_mfma_f32_16x16x32_bf16 v[64:67], v[144:147], v[176:179], v[64:67]
	v_mfma_f32_16x16x32_bf16 v[64:67], v[148:151], v[180:183], v[64:67]
	v_mfma_f32_16x16x32_bf16 v[48:51], v[144:147], v[184:187], v[48:51]
	v_mfma_f32_16x16x32_bf16 v[48:51], v[148:151], v[188:191], v[48:51]
	v_mfma_f32_16x16x32_bf16 v[32:35], v[144:147], v[192:195], v[32:35]
	v_mfma_f32_16x16x32_bf16 v[32:35], v[148:151], v[196:199], v[32:35]
	v_mfma_f32_16x16x32_bf16 v[16:19], v[144:147], v[200:203], v[16:19]
	v_mfma_f32_16x16x32_bf16 v[16:19], v[148:151], v[204:207], v[16:19]
	v_mfma_f32_16x16x32_bf16 v[12:15], v[152:155], v[200:203], v[12:15]
	v_mfma_f32_16x16x32_bf16 v[12:15], v[156:159], v[204:207], v[12:15]
	v_mfma_f32_16x16x32_bf16 v[28:31], v[152:155], v[192:195], v[28:31]
	v_mfma_f32_16x16x32_bf16 v[28:31], v[156:159], v[196:199], v[28:31]
	v_mfma_f32_16x16x32_bf16 v[44:47], v[152:155], v[184:187], v[44:47]
	v_mfma_f32_16x16x32_bf16 v[44:47], v[156:159], v[188:191], v[44:47]
	v_mfma_f32_16x16x32_bf16 v[60:63], v[152:155], v[176:179], v[60:63]
	v_mfma_f32_16x16x32_bf16 v[60:63], v[156:159], v[180:183], v[60:63]
	v_mfma_f32_16x16x32_bf16 v[56:59], v[160:163], v[176:179], v[56:59]
	v_mfma_f32_16x16x32_bf16 v[56:59], v[164:167], v[180:183], v[56:59]
	v_mfma_f32_16x16x32_bf16 v[40:43], v[160:163], v[184:187], v[40:43]
	v_mfma_f32_16x16x32_bf16 v[40:43], v[164:167], v[188:191], v[40:43]
	v_mfma_f32_16x16x32_bf16 v[24:27], v[160:163], v[192:195], v[24:27]
	v_mfma_f32_16x16x32_bf16 v[24:27], v[164:167], v[196:199], v[24:27]
	v_mfma_f32_16x16x32_bf16 v[8:11], v[160:163], v[200:203], v[8:11]
	v_mfma_f32_16x16x32_bf16 v[8:11], v[164:167], v[204:207], v[8:11]
	v_mfma_f32_16x16x32_bf16 v[4:7], v[168:171], v[200:203], v[4:7]
	v_mfma_f32_16x16x32_bf16 v[4:7], v[172:175], v[204:207], v[4:7]
	v_mfma_f32_16x16x32_bf16 v[20:23], v[168:171], v[192:195], v[20:23]
	v_mfma_f32_16x16x32_bf16 v[20:23], v[172:175], v[196:199], v[20:23]
	v_mfma_f32_16x16x32_bf16 v[36:39], v[168:171], v[184:187], v[36:39]
	v_mfma_f32_16x16x32_bf16 v[36:39], v[172:175], v[188:191], v[36:39]
	v_mfma_f32_16x16x32_bf16 v[52:55], v[168:171], v[176:179], v[52:55]
	v_mfma_f32_16x16x32_bf16 v[52:55], v[172:175], v[180:183], v[52:55]
	s_barrier
	s_setprio 0
	v_add_u32_e32 v156, s45, v142
	v_add_u32_e32 v172, s74, v142
	ds_read_b128 v[144:147], v156
	ds_read_b128 v[148:151], v156 offset:1024
	ds_read_b128 v[152:155], v156 offset:2048
	ds_read_b128 v[156:159], v156 offset:3072
	ds_read_b128 v[160:163], v172
	ds_read_b128 v[164:167], v172 offset:1024
	ds_read_b128 v[168:171], v172 offset:2048
	ds_read_b128 v[172:175], v172 offset:3072
	s_add_u32 s8, s12, s2
	s_addc_u32 s9, s13, s3
	s_mov_b32 m0, s24
	v_lshl_add_u64 v[224:225], s[8:9], 0, v[132:133]
	ds_read_b128 v[176:179], v143 offset:32768
	ds_read_b128 v[180:183], v143 offset:33792
	ds_read_b128 v[184:187], v143 offset:34816
	ds_read_b128 v[188:191], v143 offset:35840
	ds_read_b128 v[192:195], v143 offset:36864
	ds_read_b128 v[196:199], v143 offset:37888
	ds_read_b128 v[200:203], v143 offset:38912
	ds_read_b128 v[204:207], v143 offset:39936
	global_load_lds_dwordx4 v[224:225], off
	v_lshl_add_u64 v[224:225], s[8:9], 0, v[134:135]
	s_mov_b32 m0, s25
	s_nop 0
	global_load_lds_dwordx4 v[224:225], off
	s_setprio 1
	s_waitcnt vmcnt(8)
	s_waitcnt lgkmcnt(0)
	s_barrier
	v_mfma_f32_16x16x32_bf16 v[124:127], v[144:147], v[176:179], v[124:127]
	v_mfma_f32_16x16x32_bf16 v[124:127], v[148:151], v[180:183], v[124:127]
	v_mfma_f32_16x16x32_bf16 v[112:115], v[144:147], v[184:187], v[112:115]
	v_mfma_f32_16x16x32_bf16 v[112:115], v[148:151], v[188:191], v[112:115]
	v_mfma_f32_16x16x32_bf16 v[96:99], v[144:147], v[192:195], v[96:99]
	v_mfma_f32_16x16x32_bf16 v[96:99], v[148:151], v[196:199], v[96:99]
	v_mfma_f32_16x16x32_bf16 v[80:83], v[144:147], v[200:203], v[80:83]
	v_mfma_f32_16x16x32_bf16 v[80:83], v[148:151], v[204:207], v[80:83]
	v_mfma_f32_16x16x32_bf16 v[76:79], v[152:155], v[200:203], v[76:79]
	v_mfma_f32_16x16x32_bf16 v[76:79], v[156:159], v[204:207], v[76:79]
	v_mfma_f32_16x16x32_bf16 v[92:95], v[152:155], v[192:195], v[92:95]
	v_mfma_f32_16x16x32_bf16 v[92:95], v[156:159], v[196:199], v[92:95]
	v_mfma_f32_16x16x32_bf16 v[108:111], v[152:155], v[184:187], v[108:111]
	v_mfma_f32_16x16x32_bf16 v[108:111], v[156:159], v[188:191], v[108:111]
	v_mfma_f32_16x16x32_bf16 v[128:131], v[152:155], v[176:179], v[128:131]
	v_mfma_f32_16x16x32_bf16 v[128:131], v[156:159], v[180:183], v[128:131]
	v_mfma_f32_16x16x32_bf16 v[120:123], v[160:163], v[176:179], v[120:123]
	v_mfma_f32_16x16x32_bf16 v[120:123], v[164:167], v[180:183], v[120:123]
	v_mfma_f32_16x16x32_bf16 v[104:107], v[160:163], v[184:187], v[104:107]
	v_mfma_f32_16x16x32_bf16 v[104:107], v[164:167], v[188:191], v[104:107]
	v_mfma_f32_16x16x32_bf16 v[88:91], v[160:163], v[192:195], v[88:91]
	v_mfma_f32_16x16x32_bf16 v[88:91], v[164:167], v[196:199], v[88:91]
	v_mfma_f32_16x16x32_bf16 v[72:75], v[160:163], v[200:203], v[72:75]
	v_mfma_f32_16x16x32_bf16 v[72:75], v[164:167], v[204:207], v[72:75]
	v_mfma_f32_16x16x32_bf16 v[68:71], v[168:171], v[200:203], v[68:71]
	v_mfma_f32_16x16x32_bf16 v[68:71], v[172:175], v[204:207], v[68:71]
	v_mfma_f32_16x16x32_bf16 v[84:87], v[168:171], v[192:195], v[84:87]
	v_mfma_f32_16x16x32_bf16 v[84:87], v[172:175], v[196:199], v[84:87]
	v_mfma_f32_16x16x32_bf16 v[100:103], v[168:171], v[184:187], v[100:103]
	v_mfma_f32_16x16x32_bf16 v[100:103], v[172:175], v[188:191], v[100:103]
	v_mfma_f32_16x16x32_bf16 v[116:119], v[168:171], v[176:179], v[116:119]
	v_mfma_f32_16x16x32_bf16 v[116:119], v[172:175], v[180:183], v[116:119]
	s_barrier
	s_setprio 0
	s_mov_b32 m0, s26
	v_lshl_add_u64 v[208:209], v[208:209], 0, s[64:65]
	ds_read_b128 v[176:179], v143 offset:49152
	ds_read_b128 v[180:183], v143 offset:50176
	ds_read_b128 v[184:187], v143 offset:51200
	ds_read_b128 v[188:191], v143 offset:52224
	ds_read_b128 v[192:195], v143 offset:53248
	ds_read_b128 v[196:199], v143 offset:54272
	ds_read_b128 v[200:203], v143 offset:55296
	ds_read_b128 v[204:207], v143 offset:56320
	global_load_lds_dwordx4 v[208:209], off
	v_lshl_add_u64 v[208:209], v[210:211], 0, s[64:65]
	s_mov_b32 m0, s27
	s_nop 0
	global_load_lds_dwordx4 v[208:209], off
	v_lshl_add_u64 v[208:209], v[216:217], 0, s[64:65]
	s_mov_b32 m0, s37
	s_nop 0
	global_load_lds_dwordx4 v[208:209], off
	v_lshl_add_u64 v[208:209], v[218:219], 0, s[64:65]
	s_mov_b32 m0, s40
	s_nop 0
	global_load_lds_dwordx4 v[208:209], off
	v_lshl_add_u64 v[208:209], v[220:221], 0, s[64:65]
	s_mov_b32 m0, s34
	s_nop 0
	global_load_lds_dwordx4 v[208:209], off
	v_lshl_add_u64 v[208:209], v[222:223], 0, s[64:65]
	s_mov_b32 m0, s35
	s_nop 0
	global_load_lds_dwordx4 v[208:209], off
	s_setprio 1
	s_waitcnt vmcnt(8)
	s_waitcnt lgkmcnt(0)
	s_barrier
	v_mfma_f32_16x16x32_bf16 v[64:67], v[144:147], v[176:179], v[64:67]
	v_mfma_f32_16x16x32_bf16 v[64:67], v[148:151], v[180:183], v[64:67]
	v_mfma_f32_16x16x32_bf16 v[48:51], v[144:147], v[184:187], v[48:51]
	v_mfma_f32_16x16x32_bf16 v[48:51], v[148:151], v[188:191], v[48:51]
	v_mfma_f32_16x16x32_bf16 v[32:35], v[144:147], v[192:195], v[32:35]
	v_mfma_f32_16x16x32_bf16 v[32:35], v[148:151], v[196:199], v[32:35]
	v_mfma_f32_16x16x32_bf16 v[16:19], v[144:147], v[200:203], v[16:19]
	v_mfma_f32_16x16x32_bf16 v[16:19], v[148:151], v[204:207], v[16:19]
	v_mfma_f32_16x16x32_bf16 v[12:15], v[152:155], v[200:203], v[12:15]
	v_mfma_f32_16x16x32_bf16 v[12:15], v[156:159], v[204:207], v[12:15]
	v_mfma_f32_16x16x32_bf16 v[28:31], v[152:155], v[192:195], v[28:31]
	v_mfma_f32_16x16x32_bf16 v[28:31], v[156:159], v[196:199], v[28:31]
	v_mfma_f32_16x16x32_bf16 v[44:47], v[152:155], v[184:187], v[44:47]
	v_mfma_f32_16x16x32_bf16 v[44:47], v[156:159], v[188:191], v[44:47]
	v_mfma_f32_16x16x32_bf16 v[60:63], v[152:155], v[176:179], v[60:63]
	v_mfma_f32_16x16x32_bf16 v[60:63], v[156:159], v[180:183], v[60:63]
	v_mfma_f32_16x16x32_bf16 v[56:59], v[160:163], v[176:179], v[56:59]
	v_mfma_f32_16x16x32_bf16 v[56:59], v[164:167], v[180:183], v[56:59]
	v_mfma_f32_16x16x32_bf16 v[40:43], v[160:163], v[184:187], v[40:43]
	v_mfma_f32_16x16x32_bf16 v[40:43], v[164:167], v[188:191], v[40:43]
	v_mfma_f32_16x16x32_bf16 v[24:27], v[160:163], v[192:195], v[24:27]
	v_mfma_f32_16x16x32_bf16 v[24:27], v[164:167], v[196:199], v[24:27]
	v_mfma_f32_16x16x32_bf16 v[8:11], v[160:163], v[200:203], v[8:11]
	v_mfma_f32_16x16x32_bf16 v[8:11], v[164:167], v[204:207], v[8:11]
	v_mfma_f32_16x16x32_bf16 v[4:7], v[168:171], v[200:203], v[4:7]
	v_mfma_f32_16x16x32_bf16 v[4:7], v[172:175], v[204:207], v[4:7]
	v_mfma_f32_16x16x32_bf16 v[20:23], v[168:171], v[192:195], v[20:23]
	v_mfma_f32_16x16x32_bf16 v[20:23], v[172:175], v[196:199], v[20:23]
	v_mfma_f32_16x16x32_bf16 v[36:39], v[168:171], v[184:187], v[36:39]
	v_mfma_f32_16x16x32_bf16 v[36:39], v[172:175], v[188:191], v[36:39]
	v_mfma_f32_16x16x32_bf16 v[52:55], v[168:171], v[176:179], v[52:55]
	v_mfma_f32_16x16x32_bf16 v[52:55], v[172:175], v[180:183], v[52:55]
	s_barrier
	s_setprio 0
	s_cmp_ge_i32 s43, s41
	s_mov_b64 s[8:9], s[10:11]
	s_mov_b32 s12, s43
	s_cbranch_scc0 .LBB0_2329

.LBB0_2890:
	v_add_u32_e32 v4, s18, v184
	v_add_u32_e32 v8, s19, v184
	s_add_u32 s14, s48, s12
	ds_read_b128 v[28:31], v4
	ds_read_b128 v[32:35], v4 offset:16
	ds_read_b128 v[20:23], v4 offset:2048
	ds_read_b128 v[24:27], v4 offset:2064
	ds_read_b128 v[12:15], v8
	ds_read_b128 v[16:19], v8 offset:16
	ds_read_b128 v[4:7], v8 offset:2048
	ds_read_b128 v[8:11], v8 offset:2064
	s_addc_u32 s15, s49, s13
	s_add_u32 s14, s14, 0x45c00100
	s_addc_u32 s15, s15, 0
	s_add_u32 s53, s50, s12
	s_addc_u32 s56, s51, s13
	s_cmpk_eq_i32 s12, 0x700
	s_cselect_b32 s25, s11, s15
	s_cselect_b32 s24, s10, s14
	s_cselect_b32 s15, s3, s56
	s_cselect_b32 s14, s2, s53
	v_lshl_add_u64 v[210:211], v[170:171], 0, s[12:13]
	s_add_i32 m0, s37, 0xc000
	ds_read_b128 v[174:177], v185
	ds_read_b128 v[178:181], v185 offset:16
	ds_read_b128 v[186:189], v185 offset:2048
	ds_read_b128 v[190:193], v185 offset:2064
	ds_read_b128 v[194:197], v185 offset:4096
	ds_read_b128 v[198:201], v185 offset:4112
	ds_read_b128 v[202:205], v185 offset:6144
	ds_read_b128 v[206:209], v185 offset:6160
	global_load_lds_dwordx4 v[210:211], off
	v_lshl_add_u64 v[210:211], v[172:173], 0, s[12:13]
	s_add_i32 m0, s37, 0xe000
	s_nop 0
	global_load_lds_dwordx4 v[210:211], off
	s_setprio 1
	s_waitcnt vmcnt(8)
	s_waitcnt lgkmcnt(0)
	s_barrier
	v_mfma_scale_f32_16x16x128_f8f6f4 v[160:163], v[28:35], v[174:181], v[160:163], v183, v182 op_sel_hi:[0,0,0]
	v_mfma_scale_f32_16x16x128_f8f6f4 v[156:159], v[20:27], v[174:181], v[156:159], v183, v182 op_sel_hi:[0,0,0]
	v_mfma_scale_f32_16x16x128_f8f6f4 v[144:147], v[28:35], v[186:193], v[144:147], v183, v182 op_sel_hi:[0,0,0]
	v_mfma_scale_f32_16x16x128_f8f6f4 v[140:143], v[20:27], v[186:193], v[140:143], v183, v182 op_sel_hi:[0,0,0]
	v_mfma_scale_f32_16x16x128_f8f6f4 v[128:131], v[28:35], v[194:201], v[128:131], v183, v182 op_sel_hi:[0,0,0]
	v_mfma_scale_f32_16x16x128_f8f6f4 v[124:127], v[20:27], v[194:201], v[124:127], v183, v182 op_sel_hi:[0,0,0]
	v_mfma_scale_f32_16x16x128_f8f6f4 v[112:115], v[28:35], v[202:209], v[112:115], v183, v182 op_sel_hi:[0,0,0]
	v_mfma_scale_f32_16x16x128_f8f6f4 v[108:111], v[20:27], v[202:209], v[108:111], v183, v182 op_sel_hi:[0,0,0]
	v_mfma_scale_f32_16x16x128_f8f6f4 v[152:155], v[12:19], v[174:181], v[152:155], v183, v182 op_sel_hi:[0,0,0]
	v_mfma_scale_f32_16x16x128_f8f6f4 v[148:151], v[4:11], v[174:181], v[148:151], v183, v182 op_sel_hi:[0,0,0]
	v_mfma_scale_f32_16x16x128_f8f6f4 v[136:139], v[12:19], v[186:193], v[136:139], v183, v182 op_sel_hi:[0,0,0]
	v_mfma_scale_f32_16x16x128_f8f6f4 v[132:135], v[4:11], v[186:193], v[132:135], v183, v182 op_sel_hi:[0,0,0]
	v_mfma_scale_f32_16x16x128_f8f6f4 v[120:123], v[12:19], v[194:201], v[120:123], v183, v182 op_sel_hi:[0,0,0]
	v_mfma_scale_f32_16x16x128_f8f6f4 v[116:119], v[4:11], v[194:201], v[116:119], v183, v182 op_sel_hi:[0,0,0]
	v_mfma_scale_f32_16x16x128_f8f6f4 v[104:107], v[12:19], v[202:209], v[104:107], v183, v182 op_sel_hi:[0,0,0]
	v_mfma_scale_f32_16x16x128_f8f6f4 v[100:103], v[4:11], v[202:209], v[100:103], v183, v182 op_sel_hi:[0,0,0]
	s_barrier
	s_setprio 0
	s_mov_b32 m0, s23
	v_lshl_add_u64 v[174:175], s[14:15], 0, v[2:3]
	s_add_u32 s56, s14, 0x40000
	ds_read_b128 v[186:189], v185 offset:16384
	ds_read_b128 v[190:193], v185 offset:16400
	ds_read_b128 v[194:197], v185 offset:18432
	ds_read_b128 v[198:201], v185 offset:18448
	ds_read_b128 v[202:205], v185 offset:20480
	ds_read_b128 v[206:209], v185 offset:20496
	ds_read_b128 v[216:219], v185 offset:22528
	ds_read_b128 v[220:223], v185 offset:22544
	global_load_lds_dwordx4 v[174:175], off
	v_lshl_add_u64 v[176:177], s[14:15], 0, v[168:169]
	s_mov_b32 m0, s26
	s_addc_u32 s57, s15, 0
	global_load_lds_dwordx4 v[176:177], off
	v_lshl_add_u64 v[178:179], s[56:57], 0, v[2:3]
	s_mov_b32 m0, s27
	v_lshl_add_u64 v[180:181], s[24:25], 0, v[166:167]
	global_load_lds_dwordx4 v[178:179], off
	v_lshl_add_u64 v[178:179], s[56:57], 0, v[168:169]
	s_mov_b32 m0, s34
	s_nop 0
	global_load_lds_dwordx4 v[178:179], off
	v_lshl_add_u64 v[178:179], s[24:25], 0, v[164:165]
	s_mov_b32 m0, s37
	s_nop 0
	global_load_lds_dwordx4 v[178:179], off
	s_mov_b32 m0, s38
	s_nop 0
	global_load_lds_dwordx4 v[180:181], off
	s_setprio 1
	s_waitcnt vmcnt(8)
	s_waitcnt lgkmcnt(0)
	s_barrier
	v_mfma_scale_f32_16x16x128_f8f6f4 v[96:99], v[28:35], v[186:193], v[96:99], v183, v182 op_sel_hi:[0,0,0]
	v_mfma_scale_f32_16x16x128_f8f6f4 v[92:95], v[20:27], v[186:193], v[92:95], v183, v182 op_sel_hi:[0,0,0]
	v_mfma_scale_f32_16x16x128_f8f6f4 v[80:83], v[28:35], v[194:201], v[80:83], v183, v182 op_sel_hi:[0,0,0]
	v_mfma_scale_f32_16x16x128_f8f6f4 v[76:79], v[20:27], v[194:201], v[76:79], v183, v182 op_sel_hi:[0,0,0]
	v_mfma_scale_f32_16x16x128_f8f6f4 v[64:67], v[28:35], v[202:209], v[64:67], v183, v182 op_sel_hi:[0,0,0]
	v_mfma_scale_f32_16x16x128_f8f6f4 v[60:63], v[20:27], v[202:209], v[60:63], v183, v182 op_sel_hi:[0,0,0]
	v_mfma_scale_f32_16x16x128_f8f6f4 v[48:51], v[28:35], v[216:223], v[48:51], v183, v182 op_sel_hi:[0,0,0]
	v_mfma_scale_f32_16x16x128_f8f6f4 v[44:47], v[20:27], v[216:223], v[44:47], v183, v182 op_sel_hi:[0,0,0]
	v_mfma_scale_f32_16x16x128_f8f6f4 v[88:91], v[12:19], v[186:193], v[88:91], v183, v182 op_sel_hi:[0,0,0]
	v_mfma_scale_f32_16x16x128_f8f6f4 v[84:87], v[4:11], v[186:193], v[84:87], v183, v182 op_sel_hi:[0,0,0]
	v_mfma_scale_f32_16x16x128_f8f6f4 v[72:75], v[12:19], v[194:201], v[72:75], v183, v182 op_sel_hi:[0,0,0]
	v_mfma_scale_f32_16x16x128_f8f6f4 v[68:71], v[4:11], v[194:201], v[68:71], v183, v182 op_sel_hi:[0,0,0]
	v_mfma_scale_f32_16x16x128_f8f6f4 v[56:59], v[12:19], v[202:209], v[56:59], v183, v182 op_sel_hi:[0,0,0]
	v_mfma_scale_f32_16x16x128_f8f6f4 v[52:55], v[4:11], v[202:209], v[52:55], v183, v182 op_sel_hi:[0,0,0]
	v_mfma_scale_f32_16x16x128_f8f6f4 v[40:43], v[12:19], v[216:223], v[40:43], v183, v182 op_sel_hi:[0,0,0]
	v_mfma_scale_f32_16x16x128_f8f6f4 v[36:39], v[4:11], v[216:223], v[36:39], v183, v182 op_sel_hi:[0,0,0]
	s_barrier
	s_setprio 0
	v_add_u32_e32 v4, s20, v184
	v_add_u32_e32 v8, s21, v184
	ds_read_b128 v[28:31], v4
	ds_read_b128 v[32:35], v4 offset:16
	ds_read_b128 v[20:23], v4 offset:2048
	ds_read_b128 v[24:27], v4 offset:2064
	ds_read_b128 v[12:15], v8
	ds_read_b128 v[16:19], v8 offset:16
	ds_read_b128 v[4:7], v8 offset:2048
	ds_read_b128 v[8:11], v8 offset:2064
	s_add_u32 s24, s24, 0x40000
	s_addc_u32 s25, s25, 0
	s_mov_b32 m0, s39
	v_lshl_add_u64 v[210:211], s[24:25], 0, v[164:165]
	ds_read_b128 v[186:189], v185 offset:32768
	ds_read_b128 v[190:193], v185 offset:32784
	ds_read_b128 v[194:197], v185 offset:34816
	ds_read_b128 v[198:201], v185 offset:34832
	ds_read_b128 v[202:205], v185 offset:36864
	ds_read_b128 v[206:209], v185 offset:36880
	ds_read_b128 v[216:219], v185 offset:38912
	ds_read_b128 v[220:223], v185 offset:38928
	global_load_lds_dwordx4 v[210:211], off
	v_lshl_add_u64 v[210:211], s[24:25], 0, v[166:167]
	s_mov_b32 m0, s40
	s_nop 0
	global_load_lds_dwordx4 v[210:211], off
	s_setprio 1
	s_waitcnt vmcnt(8)
	s_waitcnt lgkmcnt(0)
	s_barrier
	v_mfma_scale_f32_16x16x128_f8f6f4 v[160:163], v[28:35], v[186:193], v[160:163], v183, v182 op_sel_hi:[0,0,0]
	v_mfma_scale_f32_16x16x128_f8f6f4 v[156:159], v[20:27], v[186:193], v[156:159], v183, v182 op_sel_hi:[0,0,0]
	v_mfma_scale_f32_16x16x128_f8f6f4 v[144:147], v[28:35], v[194:201], v[144:147], v183, v182 op_sel_hi:[0,0,0]
	v_mfma_scale_f32_16x16x128_f8f6f4 v[140:143], v[20:27], v[194:201], v[140:143], v183, v182 op_sel_hi:[0,0,0]
	v_mfma_scale_f32_16x16x128_f8f6f4 v[128:131], v[28:35], v[202:209], v[128:131], v183, v182 op_sel_hi:[0,0,0]
	v_mfma_scale_f32_16x16x128_f8f6f4 v[124:127], v[20:27], v[202:209], v[124:127], v183, v182 op_sel_hi:[0,0,0]
	v_mfma_scale_f32_16x16x128_f8f6f4 v[112:115], v[28:35], v[216:223], v[112:115], v183, v182 op_sel_hi:[0,0,0]
	v_mfma_scale_f32_16x16x128_f8f6f4 v[108:111], v[20:27], v[216:223], v[108:111], v183, v182 op_sel_hi:[0,0,0]
	v_mfma_scale_f32_16x16x128_f8f6f4 v[152:155], v[12:19], v[186:193], v[152:155], v183, v182 op_sel_hi:[0,0,0]
	v_mfma_scale_f32_16x16x128_f8f6f4 v[148:151], v[4:11], v[186:193], v[148:151], v183, v182 op_sel_hi:[0,0,0]
	v_mfma_scale_f32_16x16x128_f8f6f4 v[136:139], v[12:19], v[194:201], v[136:139], v183, v182 op_sel_hi:[0,0,0]
	v_mfma_scale_f32_16x16x128_f8f6f4 v[132:135], v[4:11], v[194:201], v[132:135], v183, v182 op_sel_hi:[0,0,0]
	v_mfma_scale_f32_16x16x128_f8f6f4 v[120:123], v[12:19], v[202:209], v[120:123], v183, v182 op_sel_hi:[0,0,0]
	v_mfma_scale_f32_16x16x128_f8f6f4 v[116:119], v[4:11], v[202:209], v[116:119], v183, v182 op_sel_hi:[0,0,0]
	v_mfma_scale_f32_16x16x128_f8f6f4 v[104:107], v[12:19], v[216:223], v[104:107], v183, v182 op_sel_hi:[0,0,0]
	v_mfma_scale_f32_16x16x128_f8f6f4 v[100:103], v[4:11], v[216:223], v[100:103], v183, v182 op_sel_hi:[0,0,0]
	s_barrier
	s_setprio 0
	s_mov_b32 m0, s42
	v_lshl_add_u64 v[174:175], v[174:175], 0, s[64:65]
	s_add_u32 s14, s14, 0x40080
	ds_read_b128 v[186:189], v185 offset:49152
	ds_read_b128 v[190:193], v185 offset:49168
	ds_read_b128 v[194:197], v185 offset:51200
	ds_read_b128 v[198:201], v185 offset:51216
	ds_read_b128 v[202:205], v185 offset:53248
	ds_read_b128 v[206:209], v185 offset:53264
	ds_read_b128 v[216:219], v185 offset:55296
	ds_read_b128 v[220:223], v185 offset:55312
	global_load_lds_dwordx4 v[174:175], off
	v_lshl_add_u64 v[174:175], v[176:177], 0, s[64:65]
	s_mov_b32 m0, s43
	s_addc_u32 s15, s15, 0
	global_load_lds_dwordx4 v[174:175], off
	v_lshl_add_u64 v[174:175], s[14:15], 0, v[2:3]
	s_mov_b32 m0, s46
	s_nop 0
	global_load_lds_dwordx4 v[174:175], off
	v_lshl_add_u64 v[174:175], s[14:15], 0, v[168:169]
	s_mov_b32 m0, s47
	s_nop 0
	global_load_lds_dwordx4 v[174:175], off
	v_lshl_add_u64 v[174:175], v[178:179], 0, s[64:65]
	s_mov_b32 m0, s44
	s_nop 0
	global_load_lds_dwordx4 v[174:175], off
	v_lshl_add_u64 v[174:175], v[180:181], 0, s[64:65]
	s_mov_b32 m0, s45
	s_nop 0
	global_load_lds_dwordx4 v[174:175], off
	s_setprio 1
	s_waitcnt vmcnt(8)
	s_waitcnt lgkmcnt(0)
	s_barrier
	v_mfma_scale_f32_16x16x128_f8f6f4 v[96:99], v[28:35], v[186:193], v[96:99], v183, v182 op_sel_hi:[0,0,0]
	v_mfma_scale_f32_16x16x128_f8f6f4 v[92:95], v[20:27], v[186:193], v[92:95], v183, v182 op_sel_hi:[0,0,0]
	v_mfma_scale_f32_16x16x128_f8f6f4 v[80:83], v[28:35], v[194:201], v[80:83], v183, v182 op_sel_hi:[0,0,0]
	v_mfma_scale_f32_16x16x128_f8f6f4 v[76:79], v[20:27], v[194:201], v[76:79], v183, v182 op_sel_hi:[0,0,0]
	v_mfma_scale_f32_16x16x128_f8f6f4 v[64:67], v[28:35], v[202:209], v[64:67], v183, v182 op_sel_hi:[0,0,0]
	v_mfma_scale_f32_16x16x128_f8f6f4 v[60:63], v[20:27], v[202:209], v[60:63], v183, v182 op_sel_hi:[0,0,0]
	v_mfma_scale_f32_16x16x128_f8f6f4 v[48:51], v[28:35], v[216:223], v[48:51], v183, v182 op_sel_hi:[0,0,0]
	v_mfma_scale_f32_16x16x128_f8f6f4 v[44:47], v[20:27], v[216:223], v[44:47], v183, v182 op_sel_hi:[0,0,0]
	v_mfma_scale_f32_16x16x128_f8f6f4 v[88:91], v[12:19], v[186:193], v[88:91], v183, v182 op_sel_hi:[0,0,0]
	v_mfma_scale_f32_16x16x128_f8f6f4 v[84:87], v[4:11], v[186:193], v[84:87], v183, v182 op_sel_hi:[0,0,0]
	v_mfma_scale_f32_16x16x128_f8f6f4 v[72:75], v[12:19], v[194:201], v[72:75], v183, v182 op_sel_hi:[0,0,0]
	v_mfma_scale_f32_16x16x128_f8f6f4 v[68:71], v[4:11], v[194:201], v[68:71], v183, v182 op_sel_hi:[0,0,0]
	s_add_i32 s52, s52, 2
	v_mfma_scale_f32_16x16x128_f8f6f4 v[56:59], v[12:19], v[202:209], v[56:59], v183, v182 op_sel_hi:[0,0,0]
	s_add_u32 s12, s12, 0x100
	s_addc_u32 s13, s13, 0
	v_mfma_scale_f32_16x16x128_f8f6f4 v[52:55], v[4:11], v[202:209], v[52:55], v183, v182 op_sel_hi:[0,0,0]
	s_cmp_gt_u32 s52, 13
	v_mfma_scale_f32_16x16x128_f8f6f4 v[40:43], v[12:19], v[216:223], v[40:43], v183, v182 op_sel_hi:[0,0,0]
	v_mfma_scale_f32_16x16x128_f8f6f4 v[36:39], v[4:11], v[216:223], v[36:39], v183, v182 op_sel_hi:[0,0,0]
	s_barrier
	s_setprio 0
	s_cbranch_scc0 .LBB0_2890
	s_cmpk_lt_u32 s22, 0x100
	s_cbranch_scc0 .LBB0_2893
	s_barrier

.LBB0_2896:
	v_add_u32_e32 v148, s18, v126
	v_add_u32_e32 v172, s19, v126
	s_add_u32 s12, s46, s8
	ds_read_b128 v[128:131], v148
	ds_read_b128 v[132:135], v148 offset:1024
	ds_read_b128 v[140:143], v148 offset:2048
	ds_read_b128 v[148:151], v148 offset:3072
	ds_read_b128 v[160:163], v172
	ds_read_b128 v[164:167], v172 offset:1024
	ds_read_b128 v[168:171], v172 offset:2048
	ds_read_b128 v[172:175], v172 offset:3072
	s_addc_u32 s13, s47, s9
	s_add_u32 s12, s12, 0x34400100
	s_addc_u32 s13, s13, 0
	s_add_u32 s16, s48, s8
	s_addc_u32 s51, s49, s9
	s_cmpk_eq_i32 s8, 0xf00
	s_cselect_b32 s15, s11, s13
	s_cselect_b32 s14, s10, s12
	s_cselect_b32 s13, s3, s51
	s_cselect_b32 s12, s2, s16
	v_lshl_add_u64 v[208:209], v[122:123], 0, s[8:9]
	s_add_i32 m0, s27, 0xc000
	ds_read_b128 v[176:179], v127
	ds_read_b128 v[180:183], v127 offset:1024
	ds_read_b128 v[184:187], v127 offset:2048
	ds_read_b128 v[188:191], v127 offset:3072
	ds_read_b128 v[192:195], v127 offset:4096
	ds_read_b128 v[196:199], v127 offset:5120
	ds_read_b128 v[200:203], v127 offset:6144
	ds_read_b128 v[204:207], v127 offset:7168
	global_load_lds_dwordx4 v[208:209], off
	v_lshl_add_u64 v[208:209], v[124:125], 0, s[8:9]
	s_add_i32 m0, s27, 0xe000
	s_nop 0
	global_load_lds_dwordx4 v[208:209], off
	s_setprio 1
	s_waitcnt vmcnt(8)
	s_waitcnt lgkmcnt(0)
	s_barrier
	v_mfma_f32_16x16x32_bf16 v[156:159], v[128:131], v[176:179], v[156:159]
	v_mfma_f32_16x16x32_bf16 v[156:159], v[132:135], v[180:183], v[156:159]
	v_mfma_f32_16x16x32_bf16 v[112:115], v[128:131], v[184:187], v[112:115]
	v_mfma_f32_16x16x32_bf16 v[112:115], v[132:135], v[188:191], v[112:115]
	v_mfma_f32_16x16x32_bf16 v[96:99], v[128:131], v[192:195], v[96:99]
	v_mfma_f32_16x16x32_bf16 v[96:99], v[132:135], v[196:199], v[96:99]
	v_mfma_f32_16x16x32_bf16 v[80:83], v[128:131], v[200:203], v[80:83]
	v_mfma_f32_16x16x32_bf16 v[80:83], v[132:135], v[204:207], v[80:83]
	v_mfma_f32_16x16x32_bf16 v[76:79], v[140:143], v[200:203], v[76:79]
	v_mfma_f32_16x16x32_bf16 v[76:79], v[148:151], v[204:207], v[76:79]
	v_mfma_f32_16x16x32_bf16 v[92:95], v[140:143], v[192:195], v[92:95]
	v_mfma_f32_16x16x32_bf16 v[92:95], v[148:151], v[196:199], v[92:95]
	v_mfma_f32_16x16x32_bf16 v[108:111], v[140:143], v[184:187], v[108:111]
	v_mfma_f32_16x16x32_bf16 v[108:111], v[148:151], v[188:191], v[108:111]
	v_mfma_f32_16x16x32_bf16 v[152:155], v[140:143], v[176:179], v[152:155]
	v_mfma_f32_16x16x32_bf16 v[152:155], v[148:151], v[180:183], v[152:155]
	v_mfma_f32_16x16x32_bf16 v[144:147], v[160:163], v[176:179], v[144:147]
	v_mfma_f32_16x16x32_bf16 v[144:147], v[164:167], v[180:183], v[144:147]
	v_mfma_f32_16x16x32_bf16 v[104:107], v[160:163], v[184:187], v[104:107]
	v_mfma_f32_16x16x32_bf16 v[104:107], v[164:167], v[188:191], v[104:107]
	v_mfma_f32_16x16x32_bf16 v[88:91], v[160:163], v[192:195], v[88:91]
	v_mfma_f32_16x16x32_bf16 v[88:91], v[164:167], v[196:199], v[88:91]
	v_mfma_f32_16x16x32_bf16 v[72:75], v[160:163], v[200:203], v[72:75]
	v_mfma_f32_16x16x32_bf16 v[72:75], v[164:167], v[204:207], v[72:75]
	v_mfma_f32_16x16x32_bf16 v[68:71], v[168:171], v[200:203], v[68:71]
	v_mfma_f32_16x16x32_bf16 v[68:71], v[172:175], v[204:207], v[68:71]
	v_mfma_f32_16x16x32_bf16 v[84:87], v[168:171], v[192:195], v[84:87]
	v_mfma_f32_16x16x32_bf16 v[84:87], v[172:175], v[196:199], v[84:87]
	v_mfma_f32_16x16x32_bf16 v[100:103], v[168:171], v[184:187], v[100:103]
	v_mfma_f32_16x16x32_bf16 v[100:103], v[172:175], v[188:191], v[100:103]
	v_mfma_f32_16x16x32_bf16 v[136:139], v[168:171], v[176:179], v[136:139]
	v_mfma_f32_16x16x32_bf16 v[136:139], v[172:175], v[180:183], v[136:139]
	s_barrier
	s_setprio 0
	s_mov_b32 m0, s23
	v_lshl_add_u64 v[208:209], s[12:13], 0, v[2:3]
	s_add_u32 s52, s12, 0x80000
	ds_read_b128 v[176:179], v127 offset:16384
	ds_read_b128 v[180:183], v127 offset:17408
	ds_read_b128 v[184:187], v127 offset:18432
	ds_read_b128 v[188:191], v127 offset:19456
	ds_read_b128 v[192:195], v127 offset:20480
	ds_read_b128 v[196:199], v127 offset:21504
	ds_read_b128 v[200:203], v127 offset:22528
	ds_read_b128 v[204:207], v127 offset:23552
	global_load_lds_dwordx4 v[208:209], off
	v_lshl_add_u64 v[210:211], s[12:13], 0, v[120:121]
	s_mov_b32 m0, s24
	s_addc_u32 s53, s13, 0
	global_load_lds_dwordx4 v[210:211], off
	v_lshl_add_u64 v[216:217], s[52:53], 0, v[2:3]
	s_mov_b32 m0, s25
	v_lshl_add_u64 v[218:219], s[14:15], 0, v[118:119]
	global_load_lds_dwordx4 v[216:217], off
	v_lshl_add_u64 v[216:217], s[52:53], 0, v[120:121]
	s_mov_b32 m0, s26
	s_nop 0
	global_load_lds_dwordx4 v[216:217], off
	v_lshl_add_u64 v[216:217], s[14:15], 0, v[116:117]
	s_mov_b32 m0, s27
	s_nop 0
	global_load_lds_dwordx4 v[216:217], off
	s_mov_b32 m0, s35
	s_nop 0
	global_load_lds_dwordx4 v[218:219], off
	s_setprio 1
	s_waitcnt vmcnt(8)
	s_waitcnt lgkmcnt(0)
	s_barrier
	v_mfma_f32_16x16x32_bf16 v[64:67], v[128:131], v[176:179], v[64:67]
	v_mfma_f32_16x16x32_bf16 v[64:67], v[132:135], v[180:183], v[64:67]
	v_mfma_f32_16x16x32_bf16 v[48:51], v[128:131], v[184:187], v[48:51]
	v_mfma_f32_16x16x32_bf16 v[48:51], v[132:135], v[188:191], v[48:51]
	v_mfma_f32_16x16x32_bf16 v[32:35], v[128:131], v[192:195], v[32:35]
	v_mfma_f32_16x16x32_bf16 v[32:35], v[132:135], v[196:199], v[32:35]
	v_mfma_f32_16x16x32_bf16 v[16:19], v[128:131], v[200:203], v[16:19]
	v_mfma_f32_16x16x32_bf16 v[16:19], v[132:135], v[204:207], v[16:19]
	v_mfma_f32_16x16x32_bf16 v[12:15], v[140:143], v[200:203], v[12:15]
	v_mfma_f32_16x16x32_bf16 v[12:15], v[148:151], v[204:207], v[12:15]
	v_mfma_f32_16x16x32_bf16 v[28:31], v[140:143], v[192:195], v[28:31]
	v_mfma_f32_16x16x32_bf16 v[28:31], v[148:151], v[196:199], v[28:31]
	v_mfma_f32_16x16x32_bf16 v[44:47], v[140:143], v[184:187], v[44:47]
	v_mfma_f32_16x16x32_bf16 v[44:47], v[148:151], v[188:191], v[44:47]
	v_mfma_f32_16x16x32_bf16 v[60:63], v[140:143], v[176:179], v[60:63]
	v_mfma_f32_16x16x32_bf16 v[60:63], v[148:151], v[180:183], v[60:63]
	v_mfma_f32_16x16x32_bf16 v[56:59], v[160:163], v[176:179], v[56:59]
	v_mfma_f32_16x16x32_bf16 v[56:59], v[164:167], v[180:183], v[56:59]
	v_mfma_f32_16x16x32_bf16 v[40:43], v[160:163], v[184:187], v[40:43]
	v_mfma_f32_16x16x32_bf16 v[40:43], v[164:167], v[188:191], v[40:43]
	v_mfma_f32_16x16x32_bf16 v[24:27], v[160:163], v[192:195], v[24:27]
	v_mfma_f32_16x16x32_bf16 v[24:27], v[164:167], v[196:199], v[24:27]
	v_mfma_f32_16x16x32_bf16 v[8:11], v[160:163], v[200:203], v[8:11]
	v_mfma_f32_16x16x32_bf16 v[8:11], v[164:167], v[204:207], v[8:11]
	v_mfma_f32_16x16x32_bf16 v[4:7], v[168:171], v[200:203], v[4:7]
	v_mfma_f32_16x16x32_bf16 v[4:7], v[172:175], v[204:207], v[4:7]
	v_mfma_f32_16x16x32_bf16 v[20:23], v[168:171], v[192:195], v[20:23]
	v_mfma_f32_16x16x32_bf16 v[20:23], v[172:175], v[196:199], v[20:23]
	v_mfma_f32_16x16x32_bf16 v[36:39], v[168:171], v[184:187], v[36:39]
	v_mfma_f32_16x16x32_bf16 v[36:39], v[172:175], v[188:191], v[36:39]
	v_mfma_f32_16x16x32_bf16 v[52:55], v[168:171], v[176:179], v[52:55]
	v_mfma_f32_16x16x32_bf16 v[52:55], v[172:175], v[180:183], v[52:55]
	s_barrier
	s_setprio 0
	v_add_u32_e32 v148, s20, v126
	v_add_u32_e32 v172, s21, v126
	ds_read_b128 v[128:131], v148
	ds_read_b128 v[132:135], v148 offset:1024
	ds_read_b128 v[140:143], v148 offset:2048
	ds_read_b128 v[148:151], v148 offset:3072
	ds_read_b128 v[160:163], v172
	ds_read_b128 v[164:167], v172 offset:1024
	ds_read_b128 v[168:171], v172 offset:2048
	ds_read_b128 v[172:175], v172 offset:3072
	s_add_u32 s14, s14, 0x80000
	s_addc_u32 s15, s15, 0
	s_mov_b32 m0, s37
	v_lshl_add_u64 v[220:221], s[14:15], 0, v[116:117]
	ds_read_b128 v[176:179], v127 offset:32768
	ds_read_b128 v[180:183], v127 offset:33792
	ds_read_b128 v[184:187], v127 offset:34816
	ds_read_b128 v[188:191], v127 offset:35840
	ds_read_b128 v[192:195], v127 offset:36864
	ds_read_b128 v[196:199], v127 offset:37888
	ds_read_b128 v[200:203], v127 offset:38912
	ds_read_b128 v[204:207], v127 offset:39936
	global_load_lds_dwordx4 v[220:221], off
	v_lshl_add_u64 v[220:221], s[14:15], 0, v[118:119]
	s_mov_b32 m0, s38
	s_nop 0
	global_load_lds_dwordx4 v[220:221], off
	s_setprio 1
	s_waitcnt vmcnt(8)
	s_waitcnt lgkmcnt(0)
	s_barrier
	v_mfma_f32_16x16x32_bf16 v[156:159], v[128:131], v[176:179], v[156:159]
	v_mfma_f32_16x16x32_bf16 v[156:159], v[132:135], v[180:183], v[156:159]
	v_mfma_f32_16x16x32_bf16 v[112:115], v[128:131], v[184:187], v[112:115]
	v_mfma_f32_16x16x32_bf16 v[112:115], v[132:135], v[188:191], v[112:115]
	v_mfma_f32_16x16x32_bf16 v[96:99], v[128:131], v[192:195], v[96:99]
	v_mfma_f32_16x16x32_bf16 v[96:99], v[132:135], v[196:199], v[96:99]
	v_mfma_f32_16x16x32_bf16 v[80:83], v[128:131], v[200:203], v[80:83]
	v_mfma_f32_16x16x32_bf16 v[80:83], v[132:135], v[204:207], v[80:83]
	v_mfma_f32_16x16x32_bf16 v[76:79], v[140:143], v[200:203], v[76:79]
	v_mfma_f32_16x16x32_bf16 v[76:79], v[148:151], v[204:207], v[76:79]
	v_mfma_f32_16x16x32_bf16 v[92:95], v[140:143], v[192:195], v[92:95]
	v_mfma_f32_16x16x32_bf16 v[92:95], v[148:151], v[196:199], v[92:95]
	v_mfma_f32_16x16x32_bf16 v[108:111], v[140:143], v[184:187], v[108:111]
	v_mfma_f32_16x16x32_bf16 v[108:111], v[148:151], v[188:191], v[108:111]
	v_mfma_f32_16x16x32_bf16 v[152:155], v[140:143], v[176:179], v[152:155]
	v_mfma_f32_16x16x32_bf16 v[152:155], v[148:151], v[180:183], v[152:155]
	v_mfma_f32_16x16x32_bf16 v[144:147], v[160:163], v[176:179], v[144:147]
	v_mfma_f32_16x16x32_bf16 v[144:147], v[164:167], v[180:183], v[144:147]
	v_mfma_f32_16x16x32_bf16 v[104:107], v[160:163], v[184:187], v[104:107]
	v_mfma_f32_16x16x32_bf16 v[104:107], v[164:167], v[188:191], v[104:107]
	v_mfma_f32_16x16x32_bf16 v[88:91], v[160:163], v[192:195], v[88:91]
	v_mfma_f32_16x16x32_bf16 v[88:91], v[164:167], v[196:199], v[88:91]
	v_mfma_f32_16x16x32_bf16 v[72:75], v[160:163], v[200:203], v[72:75]
	v_mfma_f32_16x16x32_bf16 v[72:75], v[164:167], v[204:207], v[72:75]
	v_mfma_f32_16x16x32_bf16 v[68:71], v[168:171], v[200:203], v[68:71]
	v_mfma_f32_16x16x32_bf16 v[68:71], v[172:175], v[204:207], v[68:71]
	v_mfma_f32_16x16x32_bf16 v[84:87], v[168:171], v[192:195], v[84:87]
	v_mfma_f32_16x16x32_bf16 v[84:87], v[172:175], v[196:199], v[84:87]
	v_mfma_f32_16x16x32_bf16 v[100:103], v[168:171], v[184:187], v[100:103]
	v_mfma_f32_16x16x32_bf16 v[100:103], v[172:175], v[188:191], v[100:103]
	v_mfma_f32_16x16x32_bf16 v[136:139], v[168:171], v[176:179], v[136:139]
	v_mfma_f32_16x16x32_bf16 v[136:139], v[172:175], v[180:183], v[136:139]
	s_barrier
	s_setprio 0
	s_mov_b32 m0, s40
	v_lshl_add_u64 v[208:209], v[208:209], 0, s[64:65]
	s_add_u32 s12, s12, 0x80080
	ds_read_b128 v[176:179], v127 offset:49152
	ds_read_b128 v[180:183], v127 offset:50176
	ds_read_b128 v[184:187], v127 offset:51200
	ds_read_b128 v[188:191], v127 offset:52224
	ds_read_b128 v[192:195], v127 offset:53248
	ds_read_b128 v[196:199], v127 offset:54272
	ds_read_b128 v[200:203], v127 offset:55296
	ds_read_b128 v[204:207], v127 offset:56320
	global_load_lds_dwordx4 v[208:209], off
	v_lshl_add_u64 v[208:209], v[210:211], 0, s[64:65]
	s_mov_b32 m0, s41
	s_addc_u32 s13, s13, 0
	global_load_lds_dwordx4 v[208:209], off
	v_lshl_add_u64 v[208:209], s[12:13], 0, v[2:3]
	s_mov_b32 m0, s44
	s_nop 0
	global_load_lds_dwordx4 v[208:209], off
	v_lshl_add_u64 v[208:209], s[12:13], 0, v[120:121]
	s_mov_b32 m0, s45
	s_nop 0
	global_load_lds_dwordx4 v[208:209], off
	v_lshl_add_u64 v[208:209], v[216:217], 0, s[64:65]
	s_mov_b32 m0, s42
	s_nop 0
	global_load_lds_dwordx4 v[208:209], off
	v_lshl_add_u64 v[208:209], v[218:219], 0, s[64:65]
	s_mov_b32 m0, s43
	s_nop 0
	global_load_lds_dwordx4 v[208:209], off
	s_setprio 1
	s_waitcnt vmcnt(8)
	s_waitcnt lgkmcnt(0)
	s_barrier
	v_mfma_f32_16x16x32_bf16 v[64:67], v[128:131], v[176:179], v[64:67]
	v_mfma_f32_16x16x32_bf16 v[64:67], v[132:135], v[180:183], v[64:67]
	v_mfma_f32_16x16x32_bf16 v[48:51], v[128:131], v[184:187], v[48:51]
	v_mfma_f32_16x16x32_bf16 v[48:51], v[132:135], v[188:191], v[48:51]
	v_mfma_f32_16x16x32_bf16 v[32:35], v[128:131], v[192:195], v[32:35]
	v_mfma_f32_16x16x32_bf16 v[32:35], v[132:135], v[196:199], v[32:35]
	v_mfma_f32_16x16x32_bf16 v[16:19], v[128:131], v[200:203], v[16:19]
	v_mfma_f32_16x16x32_bf16 v[16:19], v[132:135], v[204:207], v[16:19]
	v_mfma_f32_16x16x32_bf16 v[12:15], v[140:143], v[200:203], v[12:15]
	v_mfma_f32_16x16x32_bf16 v[12:15], v[148:151], v[204:207], v[12:15]
	v_mfma_f32_16x16x32_bf16 v[28:31], v[140:143], v[192:195], v[28:31]
	v_mfma_f32_16x16x32_bf16 v[28:31], v[148:151], v[196:199], v[28:31]
	v_mfma_f32_16x16x32_bf16 v[44:47], v[140:143], v[184:187], v[44:47]
	v_mfma_f32_16x16x32_bf16 v[44:47], v[148:151], v[188:191], v[44:47]
	v_mfma_f32_16x16x32_bf16 v[60:63], v[140:143], v[176:179], v[60:63]
	v_mfma_f32_16x16x32_bf16 v[60:63], v[148:151], v[180:183], v[60:63]
	v_mfma_f32_16x16x32_bf16 v[56:59], v[160:163], v[176:179], v[56:59]
	v_mfma_f32_16x16x32_bf16 v[56:59], v[164:167], v[180:183], v[56:59]
	v_mfma_f32_16x16x32_bf16 v[40:43], v[160:163], v[184:187], v[40:43]
	v_mfma_f32_16x16x32_bf16 v[40:43], v[164:167], v[188:191], v[40:43]
	v_mfma_f32_16x16x32_bf16 v[24:27], v[160:163], v[192:195], v[24:27]
	v_mfma_f32_16x16x32_bf16 v[24:27], v[164:167], v[196:199], v[24:27]
	v_mfma_f32_16x16x32_bf16 v[8:11], v[160:163], v[200:203], v[8:11]
	v_mfma_f32_16x16x32_bf16 v[8:11], v[164:167], v[204:207], v[8:11]
	s_add_i32 s50, s50, 2
	v_mfma_f32_16x16x32_bf16 v[4:7], v[168:171], v[200:203], v[4:7]
	v_mfma_f32_16x16x32_bf16 v[4:7], v[172:175], v[204:207], v[4:7]
	s_add_u32 s8, s8, 0x100
	s_addc_u32 s9, s9, 0
	v_mfma_f32_16x16x32_bf16 v[20:23], v[168:171], v[192:195], v[20:23]
	v_mfma_f32_16x16x32_bf16 v[20:23], v[172:175], v[196:199], v[20:23]
	s_cmp_gt_u32 s50, 29
	v_mfma_f32_16x16x32_bf16 v[36:39], v[168:171], v[184:187], v[36:39]
	v_mfma_f32_16x16x32_bf16 v[36:39], v[172:175], v[188:191], v[36:39]
	v_mfma_f32_16x16x32_bf16 v[52:55], v[168:171], v[176:179], v[52:55]
	v_mfma_f32_16x16x32_bf16 v[52:55], v[172:175], v[180:183], v[52:55]
	s_barrier
	s_setprio 0
	s_cbranch_scc0 .LBB0_2896
	s_cmpk_lt_u32 s22, 0x100
	s_cbranch_scc0 .LBB0_2899
	s_barrier

.LBB0_3116:
	v_add_u32_e32 v142, s26, v144
	ds_read_b128 v[146:149], v142
	ds_read_b128 v[150:153], v142 offset:1024
	ds_read_b128 v[154:157], v142 offset:2048
	ds_read_b128 v[158:161], v142 offset:3072
	v_add_u32_e32 v142, s40, v144
	ds_read_b128 v[162:165], v142
	ds_read_b128 v[166:169], v142 offset:1024
	ds_read_b128 v[170:173], v142 offset:2048
	ds_read_b128 v[174:177], v142 offset:3072
	s_add_u32 s18, s34, 0xfff80080
	s_addc_u32 s19, s35, -1
	s_cmp_eq_u32 s74, 28
	s_cselect_b32 s39, s13, s19
	s_cselect_b32 s38, s69, s18
	s_cselect_b32 s19, s11, s73
	s_cselect_b32 s18, s70, s71
	v_lshl_add_u64 v[142:143], s[34:35], 0, v[138:139]
	s_add_i32 m0, s43, 0xc000
	ds_read_b128 v[178:181], v145
	ds_read_b128 v[182:185], v145 offset:1024
	ds_read_b128 v[186:189], v145 offset:2048
	ds_read_b128 v[190:193], v145 offset:3072
	ds_read_b128 v[194:197], v145 offset:4096
	ds_read_b128 v[198:201], v145 offset:5120
	ds_read_b128 v[202:205], v145 offset:6144
	ds_read_b128 v[206:209], v145 offset:7168
	global_load_lds_dwordx4 v[142:143], off
	v_lshl_add_u64 v[142:143], s[34:35], 0, v[140:141]
	s_add_i32 m0, s43, 0xe000
	s_nop 0
	global_load_lds_dwordx4 v[142:143], off
	s_setprio 1
	s_waitcnt vmcnt(8)
	s_waitcnt lgkmcnt(0)
	s_barrier
	v_mfma_f32_16x16x32_bf16 v[128:131], v[146:149], v[178:181], v[128:131]
	v_mfma_f32_16x16x32_bf16 v[128:131], v[150:153], v[182:185], v[128:131]
	v_mfma_f32_16x16x32_bf16 v[112:115], v[146:149], v[186:189], v[112:115]
	v_mfma_f32_16x16x32_bf16 v[112:115], v[150:153], v[190:193], v[112:115]
	v_mfma_f32_16x16x32_bf16 v[96:99], v[146:149], v[194:197], v[96:99]
	v_mfma_f32_16x16x32_bf16 v[96:99], v[150:153], v[198:201], v[96:99]
	v_mfma_f32_16x16x32_bf16 v[80:83], v[146:149], v[202:205], v[80:83]
	v_mfma_f32_16x16x32_bf16 v[80:83], v[150:153], v[206:209], v[80:83]
	v_mfma_f32_16x16x32_bf16 v[72:75], v[154:157], v[202:205], v[72:75]
	v_mfma_f32_16x16x32_bf16 v[72:75], v[158:161], v[206:209], v[72:75]
	v_mfma_f32_16x16x32_bf16 v[88:91], v[154:157], v[194:197], v[88:91]
	v_mfma_f32_16x16x32_bf16 v[88:91], v[158:161], v[198:201], v[88:91]
	v_mfma_f32_16x16x32_bf16 v[104:107], v[154:157], v[186:189], v[104:107]
	v_mfma_f32_16x16x32_bf16 v[104:107], v[158:161], v[190:193], v[104:107]
	v_mfma_f32_16x16x32_bf16 v[120:123], v[154:157], v[178:181], v[120:123]
	v_mfma_f32_16x16x32_bf16 v[120:123], v[158:161], v[182:185], v[120:123]
	v_mfma_f32_16x16x32_bf16 v[124:127], v[162:165], v[178:181], v[124:127]
	v_mfma_f32_16x16x32_bf16 v[124:127], v[166:169], v[182:185], v[124:127]
	v_mfma_f32_16x16x32_bf16 v[108:111], v[162:165], v[186:189], v[108:111]
	v_mfma_f32_16x16x32_bf16 v[108:111], v[166:169], v[190:193], v[108:111]
	v_mfma_f32_16x16x32_bf16 v[92:95], v[162:165], v[194:197], v[92:95]
	v_mfma_f32_16x16x32_bf16 v[92:95], v[166:169], v[198:201], v[92:95]
	v_mfma_f32_16x16x32_bf16 v[76:79], v[162:165], v[202:205], v[76:79]
	v_mfma_f32_16x16x32_bf16 v[76:79], v[166:169], v[206:209], v[76:79]
	v_mfma_f32_16x16x32_bf16 v[68:71], v[170:173], v[202:205], v[68:71]
	v_mfma_f32_16x16x32_bf16 v[68:71], v[174:177], v[206:209], v[68:71]
	v_mfma_f32_16x16x32_bf16 v[84:87], v[170:173], v[194:197], v[84:87]
	v_mfma_f32_16x16x32_bf16 v[84:87], v[174:177], v[198:201], v[84:87]
	v_mfma_f32_16x16x32_bf16 v[100:103], v[170:173], v[186:189], v[100:103]
	v_mfma_f32_16x16x32_bf16 v[100:103], v[174:177], v[190:193], v[100:103]
	v_mfma_f32_16x16x32_bf16 v[116:119], v[170:173], v[178:181], v[116:119]
	v_mfma_f32_16x16x32_bf16 v[116:119], v[174:177], v[182:185], v[116:119]
	s_barrier
	s_setprio 0
	s_mov_b32 m0, s27
	v_lshl_add_u64 v[142:143], s[18:19], 0, v[2:3]
	s_add_u32 s76, s18, 0x80000
	ds_read_b128 v[178:181], v145 offset:16384
	ds_read_b128 v[182:185], v145 offset:17408
	ds_read_b128 v[186:189], v145 offset:18432
	ds_read_b128 v[190:193], v145 offset:19456
	ds_read_b128 v[194:197], v145 offset:20480
	ds_read_b128 v[198:201], v145 offset:21504
	ds_read_b128 v[202:205], v145 offset:22528
	ds_read_b128 v[206:209], v145 offset:23552
	global_load_lds_dwordx4 v[142:143], off
	v_lshl_add_u64 v[210:211], s[18:19], 0, v[132:133]
	s_mov_b32 m0, s37
	s_addc_u32 s77, s19, 0
	global_load_lds_dwordx4 v[210:211], off
	v_lshl_add_u64 v[212:213], s[76:77], 0, v[2:3]
	s_mov_b32 m0, s41
	v_lshl_add_u64 v[214:215], s[38:39], 0, v[134:135]
	global_load_lds_dwordx4 v[212:213], off
	v_lshl_add_u64 v[212:213], s[76:77], 0, v[132:133]
	s_mov_b32 m0, s42
	s_nop 0
	global_load_lds_dwordx4 v[212:213], off
	v_lshl_add_u64 v[212:213], s[38:39], 0, v[136:137]
	s_mov_b32 m0, s43
	s_nop 0
	global_load_lds_dwordx4 v[212:213], off
	s_mov_b32 m0, s44
	s_nop 0
	global_load_lds_dwordx4 v[214:215], off
	s_setprio 1
	s_waitcnt vmcnt(8)
	s_waitcnt lgkmcnt(0)
	s_barrier
	v_mfma_f32_16x16x32_bf16 v[64:67], v[146:149], v[178:181], v[64:67]
	v_mfma_f32_16x16x32_bf16 v[64:67], v[150:153], v[182:185], v[64:67]
	v_mfma_f32_16x16x32_bf16 v[48:51], v[146:149], v[186:189], v[48:51]
	v_mfma_f32_16x16x32_bf16 v[48:51], v[150:153], v[190:193], v[48:51]
	v_mfma_f32_16x16x32_bf16 v[32:35], v[146:149], v[194:197], v[32:35]
	v_mfma_f32_16x16x32_bf16 v[32:35], v[150:153], v[198:201], v[32:35]
	v_mfma_f32_16x16x32_bf16 v[16:19], v[146:149], v[202:205], v[16:19]
	v_mfma_f32_16x16x32_bf16 v[16:19], v[150:153], v[206:209], v[16:19]
	v_mfma_f32_16x16x32_bf16 v[8:11], v[154:157], v[202:205], v[8:11]
	v_mfma_f32_16x16x32_bf16 v[8:11], v[158:161], v[206:209], v[8:11]
	v_mfma_f32_16x16x32_bf16 v[24:27], v[154:157], v[194:197], v[24:27]
	v_mfma_f32_16x16x32_bf16 v[24:27], v[158:161], v[198:201], v[24:27]
	v_mfma_f32_16x16x32_bf16 v[40:43], v[154:157], v[186:189], v[40:43]
	v_mfma_f32_16x16x32_bf16 v[40:43], v[158:161], v[190:193], v[40:43]
	v_mfma_f32_16x16x32_bf16 v[56:59], v[154:157], v[178:181], v[56:59]
	v_mfma_f32_16x16x32_bf16 v[56:59], v[158:161], v[182:185], v[56:59]
	v_mfma_f32_16x16x32_bf16 v[60:63], v[162:165], v[178:181], v[60:63]
	v_mfma_f32_16x16x32_bf16 v[60:63], v[166:169], v[182:185], v[60:63]
	v_mfma_f32_16x16x32_bf16 v[44:47], v[162:165], v[186:189], v[44:47]
	v_mfma_f32_16x16x32_bf16 v[44:47], v[166:169], v[190:193], v[44:47]
	v_mfma_f32_16x16x32_bf16 v[28:31], v[162:165], v[194:197], v[28:31]
	v_mfma_f32_16x16x32_bf16 v[28:31], v[166:169], v[198:201], v[28:31]
	v_mfma_f32_16x16x32_bf16 v[12:15], v[162:165], v[202:205], v[12:15]
	v_mfma_f32_16x16x32_bf16 v[12:15], v[166:169], v[206:209], v[12:15]
	v_mfma_f32_16x16x32_bf16 v[4:7], v[170:173], v[202:205], v[4:7]
	v_mfma_f32_16x16x32_bf16 v[4:7], v[174:177], v[206:209], v[4:7]
	v_mfma_f32_16x16x32_bf16 v[20:23], v[170:173], v[194:197], v[20:23]
	v_mfma_f32_16x16x32_bf16 v[20:23], v[174:177], v[198:201], v[20:23]
	v_mfma_f32_16x16x32_bf16 v[36:39], v[170:173], v[186:189], v[36:39]
	v_mfma_f32_16x16x32_bf16 v[36:39], v[174:177], v[190:193], v[36:39]
	v_mfma_f32_16x16x32_bf16 v[52:55], v[170:173], v[178:181], v[52:55]
	v_mfma_f32_16x16x32_bf16 v[52:55], v[174:177], v[182:185], v[52:55]
	s_barrier
	s_setprio 0
	v_add_u32_e32 v158, s49, v144
	v_add_u32_e32 v174, s56, v144
	ds_read_b128 v[146:149], v158
	ds_read_b128 v[150:153], v158 offset:1024
	ds_read_b128 v[154:157], v158 offset:2048
	ds_read_b128 v[158:161], v158 offset:3072
	ds_read_b128 v[162:165], v174
	ds_read_b128 v[166:169], v174 offset:1024
	ds_read_b128 v[170:173], v174 offset:2048
	ds_read_b128 v[174:177], v174 offset:3072
	s_add_u32 s38, s38, 0x80000
	s_addc_u32 s39, s39, 0
	s_mov_b32 m0, s45
	v_lshl_add_u64 v[216:217], s[38:39], 0, v[136:137]
	ds_read_b128 v[178:181], v145 offset:32768
	ds_read_b128 v[182:185], v145 offset:33792
	ds_read_b128 v[186:189], v145 offset:34816
	ds_read_b128 v[190:193], v145 offset:35840
	ds_read_b128 v[194:197], v145 offset:36864
	ds_read_b128 v[198:201], v145 offset:37888
	ds_read_b128 v[202:205], v145 offset:38912
	ds_read_b128 v[206:209], v145 offset:39936
	global_load_lds_dwordx4 v[216:217], off
	v_lshl_add_u64 v[216:217], s[38:39], 0, v[134:135]
	s_mov_b32 m0, s46
	s_nop 0
	global_load_lds_dwordx4 v[216:217], off
	s_setprio 1
	s_waitcnt vmcnt(8)
	s_waitcnt lgkmcnt(0)
	s_barrier
	v_mfma_f32_16x16x32_bf16 v[128:131], v[146:149], v[178:181], v[128:131]
	v_mfma_f32_16x16x32_bf16 v[128:131], v[150:153], v[182:185], v[128:131]
	v_mfma_f32_16x16x32_bf16 v[112:115], v[146:149], v[186:189], v[112:115]
	v_mfma_f32_16x16x32_bf16 v[112:115], v[150:153], v[190:193], v[112:115]
	v_mfma_f32_16x16x32_bf16 v[96:99], v[146:149], v[194:197], v[96:99]
	v_mfma_f32_16x16x32_bf16 v[96:99], v[150:153], v[198:201], v[96:99]
	v_mfma_f32_16x16x32_bf16 v[80:83], v[146:149], v[202:205], v[80:83]
	v_mfma_f32_16x16x32_bf16 v[80:83], v[150:153], v[206:209], v[80:83]
	v_mfma_f32_16x16x32_bf16 v[72:75], v[154:157], v[202:205], v[72:75]
	v_mfma_f32_16x16x32_bf16 v[72:75], v[158:161], v[206:209], v[72:75]
	v_mfma_f32_16x16x32_bf16 v[88:91], v[154:157], v[194:197], v[88:91]
	v_mfma_f32_16x16x32_bf16 v[88:91], v[158:161], v[198:201], v[88:91]
	v_mfma_f32_16x16x32_bf16 v[104:107], v[154:157], v[186:189], v[104:107]
	v_mfma_f32_16x16x32_bf16 v[104:107], v[158:161], v[190:193], v[104:107]
	v_mfma_f32_16x16x32_bf16 v[120:123], v[154:157], v[178:181], v[120:123]
	v_mfma_f32_16x16x32_bf16 v[120:123], v[158:161], v[182:185], v[120:123]
	v_mfma_f32_16x16x32_bf16 v[124:127], v[162:165], v[178:181], v[124:127]
	v_mfma_f32_16x16x32_bf16 v[124:127], v[166:169], v[182:185], v[124:127]
	v_mfma_f32_16x16x32_bf16 v[108:111], v[162:165], v[186:189], v[108:111]
	v_mfma_f32_16x16x32_bf16 v[108:111], v[166:169], v[190:193], v[108:111]
	v_mfma_f32_16x16x32_bf16 v[92:95], v[162:165], v[194:197], v[92:95]
	v_mfma_f32_16x16x32_bf16 v[92:95], v[166:169], v[198:201], v[92:95]
	v_mfma_f32_16x16x32_bf16 v[76:79], v[162:165], v[202:205], v[76:79]
	v_mfma_f32_16x16x32_bf16 v[76:79], v[166:169], v[206:209], v[76:79]
	v_mfma_f32_16x16x32_bf16 v[68:71], v[170:173], v[202:205], v[68:71]
	v_mfma_f32_16x16x32_bf16 v[68:71], v[174:177], v[206:209], v[68:71]
	v_mfma_f32_16x16x32_bf16 v[84:87], v[170:173], v[194:197], v[84:87]
	v_mfma_f32_16x16x32_bf16 v[84:87], v[174:177], v[198:201], v[84:87]
	v_mfma_f32_16x16x32_bf16 v[100:103], v[170:173], v[186:189], v[100:103]
	v_mfma_f32_16x16x32_bf16 v[100:103], v[174:177], v[190:193], v[100:103]
	v_mfma_f32_16x16x32_bf16 v[116:119], v[170:173], v[178:181], v[116:119]
	v_mfma_f32_16x16x32_bf16 v[116:119], v[174:177], v[182:185], v[116:119]
	s_barrier
	s_setprio 0
	s_mov_b32 m0, s50
	v_lshl_add_u64 v[142:143], v[142:143], 0, s[64:65]
	s_add_u32 s18, s18, 0x80080
	ds_read_b128 v[178:181], v145 offset:49152
	ds_read_b128 v[182:185], v145 offset:50176
	ds_read_b128 v[186:189], v145 offset:51200
	ds_read_b128 v[190:193], v145 offset:52224
	ds_read_b128 v[194:197], v145 offset:53248
	ds_read_b128 v[198:201], v145 offset:54272
	ds_read_b128 v[202:205], v145 offset:55296
	ds_read_b128 v[206:209], v145 offset:56320
	global_load_lds_dwordx4 v[142:143], off
	v_lshl_add_u64 v[142:143], v[210:211], 0, s[64:65]
	s_mov_b32 m0, s51
	s_addc_u32 s19, s19, 0
	global_load_lds_dwordx4 v[142:143], off
	v_lshl_add_u64 v[142:143], s[18:19], 0, v[2:3]
	s_mov_b32 m0, s57
	s_nop 0
	global_load_lds_dwordx4 v[142:143], off
	v_lshl_add_u64 v[142:143], s[18:19], 0, v[132:133]
	s_mov_b32 m0, s58
	s_nop 0
	global_load_lds_dwordx4 v[142:143], off
	v_lshl_add_u64 v[142:143], v[212:213], 0, s[64:65]
	s_mov_b32 m0, s52
	s_nop 0
	global_load_lds_dwordx4 v[142:143], off
	v_lshl_add_u64 v[142:143], v[214:215], 0, s[64:65]
	s_mov_b32 m0, s53
	s_nop 0
	global_load_lds_dwordx4 v[142:143], off
	s_setprio 1
	s_waitcnt vmcnt(8)
	s_waitcnt lgkmcnt(0)
	s_barrier
	v_mfma_f32_16x16x32_bf16 v[64:67], v[146:149], v[178:181], v[64:67]
	v_mfma_f32_16x16x32_bf16 v[64:67], v[150:153], v[182:185], v[64:67]
	v_mfma_f32_16x16x32_bf16 v[48:51], v[146:149], v[186:189], v[48:51]
	v_mfma_f32_16x16x32_bf16 v[48:51], v[150:153], v[190:193], v[48:51]
	v_mfma_f32_16x16x32_bf16 v[32:35], v[146:149], v[194:197], v[32:35]
	v_mfma_f32_16x16x32_bf16 v[32:35], v[150:153], v[198:201], v[32:35]
	v_mfma_f32_16x16x32_bf16 v[16:19], v[146:149], v[202:205], v[16:19]
	v_mfma_f32_16x16x32_bf16 v[16:19], v[150:153], v[206:209], v[16:19]
	v_mfma_f32_16x16x32_bf16 v[8:11], v[154:157], v[202:205], v[8:11]
	v_mfma_f32_16x16x32_bf16 v[8:11], v[158:161], v[206:209], v[8:11]
	v_mfma_f32_16x16x32_bf16 v[24:27], v[154:157], v[194:197], v[24:27]
	v_mfma_f32_16x16x32_bf16 v[24:27], v[158:161], v[198:201], v[24:27]
	v_mfma_f32_16x16x32_bf16 v[40:43], v[154:157], v[186:189], v[40:43]
	v_mfma_f32_16x16x32_bf16 v[40:43], v[158:161], v[190:193], v[40:43]
	v_mfma_f32_16x16x32_bf16 v[56:59], v[154:157], v[178:181], v[56:59]
	v_mfma_f32_16x16x32_bf16 v[56:59], v[158:161], v[182:185], v[56:59]
	v_mfma_f32_16x16x32_bf16 v[60:63], v[162:165], v[178:181], v[60:63]
	v_mfma_f32_16x16x32_bf16 v[60:63], v[166:169], v[182:185], v[60:63]
	v_mfma_f32_16x16x32_bf16 v[44:47], v[162:165], v[186:189], v[44:47]
	v_mfma_f32_16x16x32_bf16 v[44:47], v[166:169], v[190:193], v[44:47]
	v_mfma_f32_16x16x32_bf16 v[28:31], v[162:165], v[194:197], v[28:31]
	v_mfma_f32_16x16x32_bf16 v[28:31], v[166:169], v[198:201], v[28:31]
	v_mfma_f32_16x16x32_bf16 v[12:15], v[162:165], v[202:205], v[12:15]
	v_mfma_f32_16x16x32_bf16 v[12:15], v[166:169], v[206:209], v[12:15]
	s_add_i32 s74, s74, 2
	v_mfma_f32_16x16x32_bf16 v[4:7], v[170:173], v[202:205], v[4:7]
	v_mfma_f32_16x16x32_bf16 v[4:7], v[174:177], v[206:209], v[4:7]
	s_add_u32 s34, s34, 0x100
	s_addc_u32 s35, s35, 0
	v_mfma_f32_16x16x32_bf16 v[20:23], v[170:173], v[194:197], v[20:23]
	v_mfma_f32_16x16x32_bf16 v[20:23], v[174:177], v[198:201], v[20:23]
	s_add_u32 s71, s71, 0x100
	s_addc_u32 s73, s73, 0
	v_mfma_f32_16x16x32_bf16 v[36:39], v[170:173], v[186:189], v[36:39]
	v_mfma_f32_16x16x32_bf16 v[36:39], v[174:177], v[190:193], v[36:39]
	s_cmp_gt_u32 s74, 29
	v_mfma_f32_16x16x32_bf16 v[52:55], v[170:173], v[178:181], v[52:55]
	v_mfma_f32_16x16x32_bf16 v[52:55], v[174:177], v[182:185], v[52:55]
	s_barrier
	s_setprio 0
	s_cbranch_scc0 .LBB0_3116
	s_and_b64 vcc, exec, s[8:9]
	s_cbranch_vccz .LBB0_3119
	s_barrier

.LBB0_3195:
	v_add_u32_e32 v144, s26, v249
	v_add_u32_e32 v160, s38, v249
	ds_read_b128 v[132:135], v144
	ds_read_b128 v[136:139], v144 offset:1024
	ds_read_b128 v[140:143], v144 offset:2048
	ds_read_b128 v[144:147], v144 offset:3072
	ds_read_b128 v[148:151], v160
	ds_read_b128 v[152:155], v160 offset:1024
	ds_read_b128 v[156:159], v160 offset:2048
	ds_read_b128 v[160:163], v160 offset:3072
	s_add_u32 s24, s14, 0x100
	s_addc_u32 s25, s15, 0
	s_cmpk_eq_i32 s74, 0x54
	s_cselect_b32 s35, s5, s25
	s_cselect_b32 s34, s4, s24
	s_cselect_b32 s19, s13, s73
	s_cselect_b32 s18, s12, s71
	v_lshl_add_u64 v[196:197], s[14:15], 0, v[222:223]
	s_add_i32 m0, s41, 0xc000
	ds_read_b128 v[164:167], v250
	ds_read_b128 v[168:171], v250 offset:1024
	ds_read_b128 v[172:175], v250 offset:2048
	ds_read_b128 v[176:179], v250 offset:3072
	ds_read_b128 v[180:183], v250 offset:4096
	ds_read_b128 v[184:187], v250 offset:5120
	ds_read_b128 v[188:191], v250 offset:6144
	ds_read_b128 v[192:195], v250 offset:7168
	global_load_lds_dwordx4 v[196:197], off
	v_lshl_add_u64 v[196:197], s[14:15], 0, v[224:225]
	s_add_i32 m0, s41, 0xe000
	s_nop 0
	global_load_lds_dwordx4 v[196:197], off
	s_setprio 1
	s_waitcnt vmcnt(8)
	s_waitcnt lgkmcnt(0)
	s_barrier
	v_mfma_f32_16x16x32_bf16 v[128:131], v[132:135], v[164:167], v[128:131]
	v_mfma_f32_16x16x32_bf16 v[128:131], v[136:139], v[168:171], v[128:131]
	v_mfma_f32_16x16x32_bf16 v[112:115], v[132:135], v[172:175], v[112:115]
	v_mfma_f32_16x16x32_bf16 v[112:115], v[136:139], v[176:179], v[112:115]
	v_mfma_f32_16x16x32_bf16 v[96:99], v[132:135], v[180:183], v[96:99]
	v_mfma_f32_16x16x32_bf16 v[96:99], v[136:139], v[184:187], v[96:99]
	v_mfma_f32_16x16x32_bf16 v[80:83], v[132:135], v[188:191], v[80:83]
	v_mfma_f32_16x16x32_bf16 v[80:83], v[136:139], v[192:195], v[80:83]
	v_mfma_f32_16x16x32_bf16 v[76:79], v[140:143], v[188:191], v[76:79]
	v_mfma_f32_16x16x32_bf16 v[76:79], v[144:147], v[192:195], v[76:79]
	v_mfma_f32_16x16x32_bf16 v[92:95], v[140:143], v[180:183], v[92:95]
	v_mfma_f32_16x16x32_bf16 v[92:95], v[144:147], v[184:187], v[92:95]
	v_mfma_f32_16x16x32_bf16 v[108:111], v[140:143], v[172:175], v[108:111]
	v_mfma_f32_16x16x32_bf16 v[108:111], v[144:147], v[176:179], v[108:111]
	v_mfma_f32_16x16x32_bf16 v[124:127], v[140:143], v[164:167], v[124:127]
	v_mfma_f32_16x16x32_bf16 v[124:127], v[144:147], v[168:171], v[124:127]
	v_mfma_f32_16x16x32_bf16 v[120:123], v[148:151], v[164:167], v[120:123]
	v_mfma_f32_16x16x32_bf16 v[120:123], v[152:155], v[168:171], v[120:123]
	v_mfma_f32_16x16x32_bf16 v[104:107], v[148:151], v[172:175], v[104:107]
	v_mfma_f32_16x16x32_bf16 v[104:107], v[152:155], v[176:179], v[104:107]
	v_mfma_f32_16x16x32_bf16 v[88:91], v[148:151], v[180:183], v[88:91]
	v_mfma_f32_16x16x32_bf16 v[88:91], v[152:155], v[184:187], v[88:91]
	v_mfma_f32_16x16x32_bf16 v[72:75], v[148:151], v[188:191], v[72:75]
	v_mfma_f32_16x16x32_bf16 v[72:75], v[152:155], v[192:195], v[72:75]
	v_mfma_f32_16x16x32_bf16 v[68:71], v[156:159], v[188:191], v[68:71]
	v_mfma_f32_16x16x32_bf16 v[68:71], v[160:163], v[192:195], v[68:71]
	v_mfma_f32_16x16x32_bf16 v[84:87], v[156:159], v[180:183], v[84:87]
	v_mfma_f32_16x16x32_bf16 v[84:87], v[160:163], v[184:187], v[84:87]
	v_mfma_f32_16x16x32_bf16 v[100:103], v[156:159], v[172:175], v[100:103]
	v_mfma_f32_16x16x32_bf16 v[100:103], v[160:163], v[176:179], v[100:103]
	v_mfma_f32_16x16x32_bf16 v[116:119], v[156:159], v[164:167], v[116:119]
	v_mfma_f32_16x16x32_bf16 v[116:119], v[160:163], v[168:171], v[116:119]
	s_barrier
	s_setprio 0
	s_mov_b32 m0, s27
	v_lshl_add_u64 v[196:197], s[18:19], 0, v[2:3]
	s_add_u32 s14, s18, 0x160000
	ds_read_b128 v[164:167], v250 offset:16384
	ds_read_b128 v[168:171], v250 offset:17408
	ds_read_b128 v[172:175], v250 offset:18432
	ds_read_b128 v[176:179], v250 offset:19456
	ds_read_b128 v[180:183], v250 offset:20480
	ds_read_b128 v[184:187], v250 offset:21504
	ds_read_b128 v[188:191], v250 offset:22528
	ds_read_b128 v[192:195], v250 offset:23552
	global_load_lds_dwordx4 v[196:197], off
	v_lshl_add_u64 v[198:199], s[18:19], 0, v[216:217]
	s_mov_b32 m0, s37
	s_addc_u32 s15, s19, 0
	global_load_lds_dwordx4 v[198:199], off
	v_lshl_add_u64 v[200:201], s[14:15], 0, v[2:3]
	s_mov_b32 m0, s39
	v_lshl_add_u64 v[202:203], s[34:35], 0, v[218:219]
	global_load_lds_dwordx4 v[200:201], off
	v_lshl_add_u64 v[200:201], s[14:15], 0, v[216:217]
	s_mov_b32 m0, s40
	s_nop 0
	global_load_lds_dwordx4 v[200:201], off
	v_lshl_add_u64 v[200:201], s[34:35], 0, v[220:221]
	s_mov_b32 m0, s41
	s_nop 0
	global_load_lds_dwordx4 v[200:201], off
	s_mov_b32 m0, s42
	s_nop 0
	global_load_lds_dwordx4 v[202:203], off
	s_setprio 1
	s_waitcnt vmcnt(8)
	s_waitcnt lgkmcnt(0)
	s_barrier
	v_mfma_f32_16x16x32_bf16 v[64:67], v[132:135], v[164:167], v[64:67]
	v_mfma_f32_16x16x32_bf16 v[64:67], v[136:139], v[168:171], v[64:67]
	v_mfma_f32_16x16x32_bf16 v[48:51], v[132:135], v[172:175], v[48:51]
	v_mfma_f32_16x16x32_bf16 v[48:51], v[136:139], v[176:179], v[48:51]
	v_mfma_f32_16x16x32_bf16 v[32:35], v[132:135], v[180:183], v[32:35]
	v_mfma_f32_16x16x32_bf16 v[32:35], v[136:139], v[184:187], v[32:35]
	v_mfma_f32_16x16x32_bf16 v[16:19], v[132:135], v[188:191], v[16:19]
	v_mfma_f32_16x16x32_bf16 v[16:19], v[136:139], v[192:195], v[16:19]
	v_mfma_f32_16x16x32_bf16 v[12:15], v[140:143], v[188:191], v[12:15]
	v_mfma_f32_16x16x32_bf16 v[12:15], v[144:147], v[192:195], v[12:15]
	v_mfma_f32_16x16x32_bf16 v[28:31], v[140:143], v[180:183], v[28:31]
	v_mfma_f32_16x16x32_bf16 v[28:31], v[144:147], v[184:187], v[28:31]
	v_mfma_f32_16x16x32_bf16 v[44:47], v[140:143], v[172:175], v[44:47]
	v_mfma_f32_16x16x32_bf16 v[44:47], v[144:147], v[176:179], v[44:47]
	v_mfma_f32_16x16x32_bf16 v[60:63], v[140:143], v[164:167], v[60:63]
	v_mfma_f32_16x16x32_bf16 v[60:63], v[144:147], v[168:171], v[60:63]
	v_mfma_f32_16x16x32_bf16 v[56:59], v[148:151], v[164:167], v[56:59]
	v_mfma_f32_16x16x32_bf16 v[56:59], v[152:155], v[168:171], v[56:59]
	v_mfma_f32_16x16x32_bf16 v[40:43], v[148:151], v[172:175], v[40:43]
	v_mfma_f32_16x16x32_bf16 v[40:43], v[152:155], v[176:179], v[40:43]
	v_mfma_f32_16x16x32_bf16 v[24:27], v[148:151], v[180:183], v[24:27]
	v_mfma_f32_16x16x32_bf16 v[24:27], v[152:155], v[184:187], v[24:27]
	v_mfma_f32_16x16x32_bf16 v[8:11], v[148:151], v[188:191], v[8:11]
	v_mfma_f32_16x16x32_bf16 v[8:11], v[152:155], v[192:195], v[8:11]
	v_mfma_f32_16x16x32_bf16 v[4:7], v[156:159], v[188:191], v[4:7]
	v_mfma_f32_16x16x32_bf16 v[4:7], v[160:163], v[192:195], v[4:7]
	v_mfma_f32_16x16x32_bf16 v[20:23], v[156:159], v[180:183], v[20:23]
	v_mfma_f32_16x16x32_bf16 v[20:23], v[160:163], v[184:187], v[20:23]
	v_mfma_f32_16x16x32_bf16 v[36:39], v[156:159], v[172:175], v[36:39]
	v_mfma_f32_16x16x32_bf16 v[36:39], v[160:163], v[176:179], v[36:39]
	v_mfma_f32_16x16x32_bf16 v[52:55], v[156:159], v[164:167], v[52:55]
	v_mfma_f32_16x16x32_bf16 v[52:55], v[160:163], v[168:171], v[52:55]
	s_barrier
	s_setprio 0
	v_add_u32_e32 v144, s49, v249
	v_add_u32_e32 v160, s56, v249
	ds_read_b128 v[132:135], v144
	ds_read_b128 v[136:139], v144 offset:1024
	ds_read_b128 v[140:143], v144 offset:2048
	ds_read_b128 v[144:147], v144 offset:3072
	ds_read_b128 v[148:151], v160
	ds_read_b128 v[152:155], v160 offset:1024
	ds_read_b128 v[156:159], v160 offset:2048
	ds_read_b128 v[160:163], v160 offset:3072
	s_add_u32 s14, s34, 0x160000
	s_addc_u32 s15, s35, 0
	s_mov_b32 m0, s43
	v_lshl_add_u64 v[204:205], s[14:15], 0, v[220:221]
	ds_read_b128 v[164:167], v250 offset:32768
	ds_read_b128 v[168:171], v250 offset:33792
	ds_read_b128 v[172:175], v250 offset:34816
	ds_read_b128 v[176:179], v250 offset:35840
	ds_read_b128 v[180:183], v250 offset:36864
	ds_read_b128 v[184:187], v250 offset:37888
	ds_read_b128 v[188:191], v250 offset:38912
	ds_read_b128 v[192:195], v250 offset:39936
	global_load_lds_dwordx4 v[204:205], off
	v_lshl_add_u64 v[204:205], s[14:15], 0, v[218:219]
	s_mov_b32 m0, s44
	s_nop 0
	global_load_lds_dwordx4 v[204:205], off
	s_setprio 1
	s_waitcnt vmcnt(8)
	s_waitcnt lgkmcnt(0)
	s_barrier
	v_mfma_f32_16x16x32_bf16 v[128:131], v[132:135], v[164:167], v[128:131]
	v_mfma_f32_16x16x32_bf16 v[128:131], v[136:139], v[168:171], v[128:131]
	v_mfma_f32_16x16x32_bf16 v[112:115], v[132:135], v[172:175], v[112:115]
	v_mfma_f32_16x16x32_bf16 v[112:115], v[136:139], v[176:179], v[112:115]
	v_mfma_f32_16x16x32_bf16 v[96:99], v[132:135], v[180:183], v[96:99]
	v_mfma_f32_16x16x32_bf16 v[96:99], v[136:139], v[184:187], v[96:99]
	v_mfma_f32_16x16x32_bf16 v[80:83], v[132:135], v[188:191], v[80:83]
	v_mfma_f32_16x16x32_bf16 v[80:83], v[136:139], v[192:195], v[80:83]
	v_mfma_f32_16x16x32_bf16 v[76:79], v[140:143], v[188:191], v[76:79]
	v_mfma_f32_16x16x32_bf16 v[76:79], v[144:147], v[192:195], v[76:79]
	v_mfma_f32_16x16x32_bf16 v[92:95], v[140:143], v[180:183], v[92:95]
	v_mfma_f32_16x16x32_bf16 v[92:95], v[144:147], v[184:187], v[92:95]
	v_mfma_f32_16x16x32_bf16 v[108:111], v[140:143], v[172:175], v[108:111]
	v_mfma_f32_16x16x32_bf16 v[108:111], v[144:147], v[176:179], v[108:111]
	v_mfma_f32_16x16x32_bf16 v[124:127], v[140:143], v[164:167], v[124:127]
	v_mfma_f32_16x16x32_bf16 v[124:127], v[144:147], v[168:171], v[124:127]
	v_mfma_f32_16x16x32_bf16 v[120:123], v[148:151], v[164:167], v[120:123]
	v_mfma_f32_16x16x32_bf16 v[120:123], v[152:155], v[168:171], v[120:123]
	v_mfma_f32_16x16x32_bf16 v[104:107], v[148:151], v[172:175], v[104:107]
	v_mfma_f32_16x16x32_bf16 v[104:107], v[152:155], v[176:179], v[104:107]
	v_mfma_f32_16x16x32_bf16 v[88:91], v[148:151], v[180:183], v[88:91]
	v_mfma_f32_16x16x32_bf16 v[88:91], v[152:155], v[184:187], v[88:91]
	v_mfma_f32_16x16x32_bf16 v[72:75], v[148:151], v[188:191], v[72:75]
	v_mfma_f32_16x16x32_bf16 v[72:75], v[152:155], v[192:195], v[72:75]
	v_mfma_f32_16x16x32_bf16 v[68:71], v[156:159], v[188:191], v[68:71]
	v_mfma_f32_16x16x32_bf16 v[68:71], v[160:163], v[192:195], v[68:71]
	v_mfma_f32_16x16x32_bf16 v[84:87], v[156:159], v[180:183], v[84:87]
	v_mfma_f32_16x16x32_bf16 v[84:87], v[160:163], v[184:187], v[84:87]
	v_mfma_f32_16x16x32_bf16 v[100:103], v[156:159], v[172:175], v[100:103]
	v_mfma_f32_16x16x32_bf16 v[100:103], v[160:163], v[176:179], v[100:103]
	v_mfma_f32_16x16x32_bf16 v[116:119], v[156:159], v[164:167], v[116:119]
	v_mfma_f32_16x16x32_bf16 v[116:119], v[160:163], v[168:171], v[116:119]
	s_barrier
	s_setprio 0
	s_mov_b32 m0, s50
	v_lshl_add_u64 v[196:197], v[196:197], 0, s[64:65]
	s_add_u32 s14, s18, 0x160080
	ds_read_b128 v[164:167], v250 offset:49152
	ds_read_b128 v[168:171], v250 offset:50176
	ds_read_b128 v[172:175], v250 offset:51200
	ds_read_b128 v[176:179], v250 offset:52224
	ds_read_b128 v[180:183], v250 offset:53248
	ds_read_b128 v[184:187], v250 offset:54272
	ds_read_b128 v[188:191], v250 offset:55296
	ds_read_b128 v[192:195], v250 offset:56320
	global_load_lds_dwordx4 v[196:197], off
	v_lshl_add_u64 v[196:197], v[198:199], 0, s[64:65]
	s_mov_b32 m0, s51
	s_addc_u32 s15, s19, 0
	global_load_lds_dwordx4 v[196:197], off
	v_lshl_add_u64 v[196:197], s[14:15], 0, v[2:3]
	s_mov_b32 m0, s57
	s_nop 0
	global_load_lds_dwordx4 v[196:197], off
	v_lshl_add_u64 v[196:197], s[14:15], 0, v[216:217]
	s_mov_b32 m0, s58
	s_nop 0
	global_load_lds_dwordx4 v[196:197], off
	v_lshl_add_u64 v[196:197], v[200:201], 0, s[64:65]
	s_mov_b32 m0, s52
	s_nop 0
	global_load_lds_dwordx4 v[196:197], off
	v_lshl_add_u64 v[196:197], v[202:203], 0, s[64:65]
	s_mov_b32 m0, s53
	s_nop 0
	global_load_lds_dwordx4 v[196:197], off
	s_setprio 1
	s_waitcnt vmcnt(8)
	s_waitcnt lgkmcnt(0)
	s_barrier
	v_mfma_f32_16x16x32_bf16 v[64:67], v[132:135], v[164:167], v[64:67]
	v_mfma_f32_16x16x32_bf16 v[64:67], v[136:139], v[168:171], v[64:67]
	v_mfma_f32_16x16x32_bf16 v[48:51], v[132:135], v[172:175], v[48:51]
	v_mfma_f32_16x16x32_bf16 v[48:51], v[136:139], v[176:179], v[48:51]
	v_mfma_f32_16x16x32_bf16 v[32:35], v[132:135], v[180:183], v[32:35]
	v_mfma_f32_16x16x32_bf16 v[32:35], v[136:139], v[184:187], v[32:35]
	v_mfma_f32_16x16x32_bf16 v[16:19], v[132:135], v[188:191], v[16:19]
	v_mfma_f32_16x16x32_bf16 v[16:19], v[136:139], v[192:195], v[16:19]
	v_mfma_f32_16x16x32_bf16 v[12:15], v[140:143], v[188:191], v[12:15]
	v_mfma_f32_16x16x32_bf16 v[12:15], v[144:147], v[192:195], v[12:15]
	v_mfma_f32_16x16x32_bf16 v[28:31], v[140:143], v[180:183], v[28:31]
	v_mfma_f32_16x16x32_bf16 v[28:31], v[144:147], v[184:187], v[28:31]
	v_mfma_f32_16x16x32_bf16 v[44:47], v[140:143], v[172:175], v[44:47]
	v_mfma_f32_16x16x32_bf16 v[44:47], v[144:147], v[176:179], v[44:47]
	v_mfma_f32_16x16x32_bf16 v[60:63], v[140:143], v[164:167], v[60:63]
	v_mfma_f32_16x16x32_bf16 v[60:63], v[144:147], v[168:171], v[60:63]
	v_mfma_f32_16x16x32_bf16 v[56:59], v[148:151], v[164:167], v[56:59]
	v_mfma_f32_16x16x32_bf16 v[56:59], v[152:155], v[168:171], v[56:59]
	v_mfma_f32_16x16x32_bf16 v[40:43], v[148:151], v[172:175], v[40:43]
	v_mfma_f32_16x16x32_bf16 v[40:43], v[152:155], v[176:179], v[40:43]
	v_mfma_f32_16x16x32_bf16 v[24:27], v[148:151], v[180:183], v[24:27]
	v_mfma_f32_16x16x32_bf16 v[24:27], v[152:155], v[184:187], v[24:27]
	v_mfma_f32_16x16x32_bf16 v[8:11], v[148:151], v[188:191], v[8:11]
	v_mfma_f32_16x16x32_bf16 v[8:11], v[152:155], v[192:195], v[8:11]
	s_add_i32 s74, s74, 2
	v_mfma_f32_16x16x32_bf16 v[4:7], v[156:159], v[188:191], v[4:7]
	v_mfma_f32_16x16x32_bf16 v[4:7], v[160:163], v[192:195], v[4:7]
	s_add_u32 s71, s71, 0x100
	s_addc_u32 s73, s73, 0
	v_mfma_f32_16x16x32_bf16 v[20:23], v[156:159], v[180:183], v[20:23]
	v_mfma_f32_16x16x32_bf16 v[20:23], v[160:163], v[184:187], v[20:23]
	s_cmpk_gt_u32 s74, 0x55
	v_mfma_f32_16x16x32_bf16 v[36:39], v[156:159], v[172:175], v[36:39]
	v_mfma_f32_16x16x32_bf16 v[36:39], v[160:163], v[176:179], v[36:39]
	v_mfma_f32_16x16x32_bf16 v[52:55], v[156:159], v[164:167], v[52:55]
	v_mfma_f32_16x16x32_bf16 v[52:55], v[160:163], v[168:171], v[52:55]
	s_barrier
	s_setprio 0
	s_mov_b64 s[14:15], s[24:25]
	s_cbranch_scc0 .LBB0_3195
	s_and_b64 vcc, exec, s[10:11]
	s_cbranch_vccz .LBB0_3198
	s_barrier
